# attention both layers: running-max reference folded into the C operand of the first QK MFMA (64 VALU adds per key-tile pair removed); L1 last-pair temporaries moved to dead staging registers
# baseline (speedup 1.0000x reference)
; #define LAS __attribute__((address_space(3)))
; #define ATT_LOAD(k0_, k1_, v_, tt) do { const char* kg_ = Kg + (size_t)(tt) * 12288; const char* vg_ = Vg + (size_t)(tt) * 8192; \
;             k0_ = *(const u32x4*)(kg_ + tid_ * 16); if (tid_ < 256) k1_ = *(const u32x4*)(kg_ + (tid_ + 512) * 16); v_ = *(const u32x4*)(vg_ + tid_ * 16); } while (0)
; #define ATT_WRITE(k0_, k1_, v_, bo) do { *(LAS u32x4*)(sm + (bo) + koff0) = k0_; if (tid_ < 256) *(LAS u32x4*)(sm + (bo) + koff1) = k1_; *(LAS u32x4*)(sm + (bo) + voff) = v_; } while (0)
; __device__ __forceinline__ void ph_attn_mfma(unsigned char* lds_, const bf16_t* Q, const bf16_t* Kb, const bf16_t* Vb, bf16_t* Z, int with_ctx, int u0, int ustep) { PH_IDS;
;     ...
;         f32x16 a0, a1, b0, b1;
; #pragma unroll
;         for (int r = 0; r < 16; ++r) { a0[r] = 0.f; a1[r] = 0.f; }
;         { const LAS char* kq0 = sm + r32 * KP_A + 16 * hi;
; #pragma unroll
;           for (int st = 0; st < 6; ++st) { const bf16x8 k0 = *(const LAS bf16x8*)(kq0 + 32 * st), k1 = *(const LAS bf16x8*)(kq0 + 32 * KP_A + 32 * st);
;               a0 = __builtin_amdgcn_mfma_f32_32x32x16_bf16(k0, qf[st], a0, 0, 0, 0); a1 = __builtin_amdgcn_mfma_f32_32x32x16_bf16(k1, qf[st], a1, 0, 0, 0); } }
;         float tmA = att_max(a0, a1);
;         int cur = 0;
;         for (int p = 0; p < npair; ++p) {
;             const int nxt = cur == 4 * BUF_A ? 0 : cur + 2 * BUF_A;
;             const bool more = p + 1 < npair;
;             if (more) { ATT_WRITE(ka0, ka1, va, nxt); ATT_WRITE(kb0, kb1, vb, nxt + BUF_A); }
;             if (p + 2 < npair) { ATT_LOAD(ka0, ka1, va, 2 * p + 4); ATT_LOAD(kb0, kb1, vb, 2 * p + 5); }
;             bf16x8 pf[4];
;             att_shift(tmA, p == 0, mrun, lsum, o0, o1);
;             att_qk_exp(sm + cur + BUF_A + r32 * KP_A + 16 * hi, qf, -mrun, b0, b1, a0, a1, lsum, pf);
.LBB0_1026:
	s_or_b64 exec, exec, s[8:9]
	v_add_co_u32_e32 v2, vcc, 0x6000, v20
	v_mul_u32_u24_e32 v187, 0xd0, v131
	s_nop 0
	v_addc_co_u32_e32 v3, vcc, 0, v21, vcc
	global_load_dwordx4 v[176:179], v[2:3], off
	v_add3_u32 v188, 0, v187, v180
	s_waitcnt lgkmcnt(0)
	s_barrier
	ds_read_b128 v[2:5], v188
	ds_read_b128 v[40:43], v188 offset:32
	s_waitcnt lgkmcnt(1)
	v_mfma_f32_32x32x16_bf16 v[2:17], v[2:5], v[132:135], 0
	ds_read_b128 v[18:21], v188 offset:6656
	ds_read_b128 v[44:47], v188 offset:6688
	v_lshlrev_b32_e32 v35, 1, v36
	v_and_b32_e32 v36, 24, v38
	v_and_or_b32 v35, v35, 32, v36
	v_lshlrev_b32_e32 v36, 8, v37
	v_and_b32_e32 v34, 0xc0, v34
	v_lshlrev_b32_e32 v186, 3, v37
	s_waitcnt lgkmcnt(1)
	v_mfma_f32_32x32x16_bf16 v[18:33], v[18:21], v[132:135], 0
	v_or3_b32 v189, v36, v34, v35
	s_mov_b32 s8, 0
	s_mov_b32 s22, s8
	s_mov_b32 s23, s8
	s_mov_b32 s9, s8
	s_mov_b32 s10, s8
	s_mov_b32 s11, s8
	v_mfma_f32_32x32x16_bf16 v[2:17], v[40:43], v[136:139], v[2:17]
	s_mov_b32 s12, s8
	s_mov_b32 s13, s8
	s_mov_b32 s14, s8
	s_mov_b32 s15, s8
	s_mov_b32 s16, s8
	s_mov_b32 s17, s8
	s_mov_b32 s18, s8
	s_waitcnt lgkmcnt(0)
	v_mfma_f32_32x32x16_bf16 v[18:33], v[44:47], v[136:139], v[18:33]
	ds_read_b128 v[40:43], v188 offset:64
	ds_read_b128 v[44:47], v188 offset:96
	s_mov_b32 s19, s8
	s_mov_b32 s20, s8
	s_mov_b32 s21, s8
	v_mov_b64_e32 v[112:113], s[22:23]
	v_mov_b64_e32 v[110:111], s[20:21]
	v_mov_b64_e32 v[108:109], s[18:19]
	s_waitcnt lgkmcnt(1)
	v_mfma_f32_32x32x16_bf16 v[2:17], v[40:43], v[140:143], v[2:17]
	ds_read_b128 v[40:43], v188 offset:6720
	ds_read_b128 v[48:51], v188 offset:6752
	v_mov_b64_e32 v[106:107], s[16:17]
	v_mov_b64_e32 v[104:105], s[14:15]
	v_mov_b64_e32 v[102:103], s[12:13]
	v_mov_b64_e32 v[100:101], s[10:11]
	v_mov_b64_e32 v[98:99], s[8:9]
	v_mov_b64_e32 v[128:129], v[112:113]
	s_waitcnt lgkmcnt(1)
	v_mfma_f32_32x32x16_bf16 v[18:33], v[40:43], v[140:143], v[18:33]
	ds_read_b128 v[40:43], v188 offset:128
	s_mov_b64 s[6:7], 0
	s_mov_b64 s[12:13], -1
	v_mov_b32_e32 v66, 0
	v_mov_b32_e32 v190, 0
	v_mov_b64_e32 v[226:227], 0
	v_mov_b64_e32 v[228:229], 0
	v_mov_b64_e32 v[230:231], 0
	v_mov_b64_e32 v[232:233], 0
	v_mov_b64_e32 v[234:235], 0
	v_mov_b64_e32 v[236:237], 0
	v_mov_b64_e32 v[238:239], 0
	v_mov_b64_e32 v[240:241], 0
	v_mov_b64_e32 v[126:127], v[110:111]
	v_mov_b64_e32 v[124:125], v[108:109]
	v_mfma_f32_32x32x16_bf16 v[2:17], v[44:47], v[144:147], v[2:17]
	ds_read_b128 v[34:37], v188 offset:6784
	ds_read_b128 v[44:47], v188 offset:160
	v_mov_b64_e32 v[122:123], v[106:107]
	v_mov_b64_e32 v[120:121], v[104:105]
	v_mov_b64_e32 v[118:119], v[102:103]
	v_mov_b64_e32 v[116:117], v[100:101]
	v_mov_b64_e32 v[114:115], v[98:99]
	s_waitcnt lgkmcnt(3)
	v_mfma_f32_32x32x16_bf16 v[18:33], v[48:51], v[144:147], v[18:33]
	s_waitcnt lgkmcnt(2)
	v_mfma_f32_32x32x16_bf16 v[2:17], v[40:43], v[148:151], v[2:17]
	ds_read_b128 v[38:41], v188 offset:6816
	s_waitcnt lgkmcnt(2)
	v_mfma_f32_32x32x16_bf16 v[18:33], v[34:37], v[148:151], v[18:33]
	s_waitcnt lgkmcnt(1)
	v_mfma_f32_32x32x16_bf16 v[2:17], v[44:47], v[152:155], v[2:17]
	s_waitcnt lgkmcnt(0)
	v_mfma_f32_32x32x16_bf16 v[18:33], v[38:41], v[152:155], v[18:33]
	s_nop 9
	v_max_f32_e32 v34, v3, v3
	v_max_f32_e32 v35, v2, v2
	v_max_f32_e32 v34, v35, v34
	v_max3_f32 v35, v4, v5, v19
	v_max3_f32 v34, v34, v18, v20
	v_max3_f32 v34, v34, v21, v6
	v_max3_f32 v35, v35, v8, v9
	v_max3_f32 v34, v34, v7, v22
	v_max3_f32 v35, v35, v24, v25
	v_max3_f32 v34, v34, v23, v10
	v_max3_f32 v35, v35, v12, v13
	v_max3_f32 v34, v34, v11, v26
	v_max3_f32 v35, v35, v28, v29
	v_max3_f32 v34, v34, v27, v14
	v_max3_f32 v35, v35, v16, v17
	v_max3_f32 v34, v34, v15, v30
	v_max3_f32 v35, v35, v32, v33
	v_max3_f32 v191, v34, v31, v35
.LBB0_1027:
	s_xor_b64 s[10:11], s[12:13], -1
	s_add_i32 s9, s8, 0xa800
	s_cmp_lg_u32 s8, 0x15000
	s_cselect_b32 s18, s9, 0
	s_and_b64 vcc, exec, s[10:11]
	s_mov_b64 s[14:15], 0
	s_mov_b64 s[16:17], -1
	s_cbranch_vccz .LBB0_1039
	v_add_f32_e32 v194, 0x41000000, v190
	v_cmp_lt_f32_e32 vcc, 0x41000000, v191
	s_cmp_lg_u64 vcc, 0
	s_cselect_b64 s[14:15], -1, 0
	s_cbranch_execz .LBB0_1040

; #define LAS __attribute__((address_space(3)))
; __device__ __forceinline__ bf16x8 pack_p(const f32x16& p, int base) { u32x4 w; w.x = pk2(p[base], p[base + 1]); w.y = pk2(p[base + 2], p[base + 3]); w.z = pk2(p[base + 4], p[base + 5]); w.w = pk2(p[base + 6], p[base + 7]); return __builtin_bit_cast(bf16x8, w); }
; __device__ __forceinline__ float vadd1(float a, float b) { float r; asm("v_add_f32 %0, %1, %2" : "=v"(r) : "v"(a), "v"(b)); return r; }
; __device__ __forceinline__ void att_shift(float tm, bool first, float& mrun, float& lsum, fa::f32x16& o0, fa::f32x16& o1) {
;     if (first || __any(tm > mrun + 8.f)) {
;         tm = fmaxf(tm, __shfl_xor(tm, 32));
;         const float dl = first ? 0.f : fmaxf(tm - mrun, 0.f), alpha = __builtin_amdgcn_exp2f(-dl);
;         mrun = first ? tm : mrun + dl; lsum *= alpha;
; #pragma unroll
;         for (int r = 0; r < 16; ++r) { o0[r] *= alpha; o1[r] *= alpha; }
;     }
; }
; __device__ __forceinline__ void att_qk_exp(const LAS char* kb, const bf16x8 (&qf)[6], float nm, fa::f32x16& n0, fa::f32x16& n1, fa::f32x16& p0, fa::f32x16& p1, float& lsum, bf16x8 (&pf)[4]) {
;     const fa::f32x16 zero = {0.f, 0.f, 0.f, 0.f, 0.f, 0.f, 0.f, 0.f, 0.f, 0.f, 0.f, 0.f, 0.f, 0.f, 0.f, 0.f};
;     bf16x8 kc0 = *(const LAS bf16x8*)kb, kc1 = *(const LAS bf16x8*)(kb + 32 * fa::KP_A);
;     float ps = 0.f, ps2 = 0.f;
; #pragma unroll
;     for (int st = 0; st < 6; ++st) {
;         bf16x8 kn0 = kc0, kn1 = kc1;
;         if (st < 5) { kn0 = *(const LAS bf16x8*)(kb + 32 * (st + 1)); kn1 = *(const LAS bf16x8*)(kb + 32 * fa::KP_A + 32 * (st + 1)); }
;         n0 = __builtin_amdgcn_mfma_f32_32x32x16_bf16(kc0, qf[st], st == 0 ? zero : n0, 0, 0, 0);
;         n1 = __builtin_amdgcn_mfma_f32_32x32x16_bf16(kc1, qf[st], st == 0 ? zero : n1, 0, 0, 0);
;         constexpr int lo[7] = {0, 2, 6, 8, 10, 14, 16};
; #pragma unroll
;         for (int r = lo[st]; r < lo[st + 1]; ++r) {
;             p0[r] = __builtin_amdgcn_exp2f(vadd1(p0[r], nm)); p1[r] = __builtin_amdgcn_exp2f(vadd1(p1[r], nm));
;             ps += p0[r]; ps += p1[r]; }
;         kc0 = kn0; kc1 = kn1;
;         __builtin_amdgcn_sched_barrier(0);
;     }
;     lsum += ps + ps2;
;     pf[0] = fa::pack_p(p0, 0); pf[1] = fa::pack_p(p0, 8); pf[2] = fa::pack_p(p1, 0); pf[3] = fa::pack_p(p1, 8);
; }
.LBB0_1030:
	v_and_b32_e32 v35, 64, v1
	v_xor_b32_e32 v34, 32, v1
	v_add_u32_e32 v35, 64, v35
	v_cmp_lt_i32_e32 vcc, v34, v35
	v_max_f32_e32 v35, v191, v191
	s_nop 0
	v_cndmask_b32_e32 v34, v1, v34, vcc
	v_lshlrev_b32_e32 v34, 2, v34
	ds_bpermute_b32 v34, v34, v191
	s_waitcnt lgkmcnt(0)
	v_max_f32_e32 v34, v34, v34
	v_max_f32_e32 v35, v35, v34
	v_mov_b32_e32 v34, v35
	v_max_f32_e32 v36, 0, v34
	v_cndmask_b32_e64 v242, v36, v35, s[12:13]
	v_cndmask_b32_e64 v34, -v36, v212, s[12:13]
	v_exp_f32_e32 v34, v34
	v_add_f32_e32 v36, v190, v36
	v_cndmask_b32_e64 v190, v36, v35, s[12:13]
	v_add_f32_e32 v194, 0x41000000, v190
	v_mul_f32_e32 v66, v66, v34
	v_pk_mul_f32 v[128:129], v[128:129], v[34:35] op_sel_hi:[1,0]
	v_pk_mul_f32 v[126:127], v[126:127], v[34:35] op_sel_hi:[1,0]
	v_pk_mul_f32 v[124:125], v[124:125], v[34:35] op_sel_hi:[1,0]
	v_pk_mul_f32 v[122:123], v[122:123], v[34:35] op_sel_hi:[1,0]
	v_pk_mul_f32 v[120:121], v[120:121], v[34:35] op_sel_hi:[1,0]
	v_pk_mul_f32 v[118:119], v[118:119], v[34:35] op_sel_hi:[1,0]
	v_pk_mul_f32 v[116:117], v[116:117], v[34:35] op_sel_hi:[1,0]
	v_pk_mul_f32 v[114:115], v[114:115], v[34:35] op_sel_hi:[1,0]
	v_pk_mul_f32 v[112:113], v[112:113], v[34:35] op_sel_hi:[1,0]
	v_pk_mul_f32 v[110:111], v[110:111], v[34:35] op_sel_hi:[1,0]
	v_pk_mul_f32 v[108:109], v[108:109], v[34:35] op_sel_hi:[1,0]
	v_pk_mul_f32 v[106:107], v[106:107], v[34:35] op_sel_hi:[1,0]
	v_pk_mul_f32 v[104:105], v[104:105], v[34:35] op_sel_hi:[1,0]
	v_pk_mul_f32 v[102:103], v[102:103], v[34:35] op_sel_hi:[1,0]
	v_pk_mul_f32 v[100:101], v[100:101], v[34:35] op_sel_hi:[1,0]
	v_pk_mul_f32 v[98:99], v[98:99], v[34:35] op_sel_hi:[1,0]
	v_sub_f32_e32 v2, v2, v242
	v_sub_f32_e32 v3, v3, v242
	v_sub_f32_e32 v4, v4, v242
	v_sub_f32_e32 v5, v5, v242
	v_sub_f32_e32 v6, v6, v242
	v_sub_f32_e32 v7, v7, v242
	v_sub_f32_e32 v8, v8, v242
	v_sub_f32_e32 v9, v9, v242
	v_sub_f32_e32 v10, v10, v242
	v_sub_f32_e32 v11, v11, v242
	v_sub_f32_e32 v12, v12, v242
	v_sub_f32_e32 v13, v13, v242
	v_sub_f32_e32 v14, v14, v242
	v_sub_f32_e32 v15, v15, v242
	v_sub_f32_e32 v16, v16, v242
	v_sub_f32_e32 v17, v17, v242
	v_sub_f32_e32 v18, v18, v242
	v_sub_f32_e32 v19, v19, v242
	v_sub_f32_e32 v20, v20, v242
	v_sub_f32_e32 v21, v21, v242
	v_sub_f32_e32 v22, v22, v242
	v_sub_f32_e32 v23, v23, v242
	v_sub_f32_e32 v24, v24, v242
	v_sub_f32_e32 v25, v25, v242
	v_sub_f32_e32 v26, v26, v242
	v_sub_f32_e32 v27, v27, v242
	v_sub_f32_e32 v28, v28, v242
	v_sub_f32_e32 v29, v29, v242
	v_sub_f32_e32 v30, v30, v242
	v_sub_f32_e32 v31, v31, v242
	v_sub_f32_e32 v32, v32, v242
	v_sub_f32_e32 v33, v33, v242
	v_sub_f32_e32 v226, v226, v242
	v_sub_f32_e32 v227, v227, v242
	v_sub_f32_e32 v228, v228, v242
	v_sub_f32_e32 v229, v229, v242
	v_sub_f32_e32 v230, v230, v242
	v_sub_f32_e32 v231, v231, v242
	v_sub_f32_e32 v232, v232, v242
	v_sub_f32_e32 v233, v233, v242
	v_sub_f32_e32 v234, v234, v242
	v_sub_f32_e32 v235, v235, v242
	v_sub_f32_e32 v236, v236, v242
	v_sub_f32_e32 v237, v237, v242
	v_sub_f32_e32 v238, v238, v242
	v_sub_f32_e32 v239, v239, v242
	v_sub_f32_e32 v240, v240, v242
	v_sub_f32_e32 v241, v241, v242
.LBB0_1031:
	s_add_i32 s8, s8, 0
	v_add3_u32 v67, s8, v187, v180
	ds_read_b128 v[34:37], v67 offset:21504
	ds_read_b128 v[50:53], v67 offset:28160
	ds_read_b128 v[68:71], v67 offset:21536
	s_waitcnt lgkmcnt(1)
	v_mfma_f32_32x32x16_bf16 v[50:65], v[50:53], v[132:135], v[226:241]
	ds_read_b128 v[72:75], v67 offset:28192
	v_exp_f32_e32 v2, v2
	v_exp_f32_e32 v18, v18
	v_exp_f32_e32 v3, v3
	v_mfma_f32_32x32x16_bf16 v[34:49], v[34:37], v[132:135], v[226:241]
	v_exp_f32_e32 v19, v19
	s_waitcnt lgkmcnt(1)
	v_mfma_f32_32x32x16_bf16 v[34:49], v[68:71], v[136:139], v[34:49]
	ds_read_b128 v[76:79], v67 offset:21568
	ds_read_b128 v[80:83], v67 offset:28224
	s_waitcnt lgkmcnt(2)
	v_mfma_f32_32x32x16_bf16 v[50:65], v[72:75], v[136:139], v[50:65]
	v_exp_f32_e32 v4, v4
	v_exp_f32_e32 v20, v20
	v_exp_f32_e32 v5, v5
	v_exp_f32_e32 v21, v21
	v_exp_f32_e32 v6, v6
	v_exp_f32_e32 v22, v22
	v_exp_f32_e32 v7, v7
	v_exp_f32_e32 v23, v23
	s_waitcnt lgkmcnt(1)
	v_mfma_f32_32x32x16_bf16 v[34:49], v[76:79], v[140:143], v[34:49]
	ds_read_b128 v[68:71], v67 offset:21600
	ds_read_b128 v[72:75], v67 offset:28256
	s_nop 0
	v_exp_f32_e32 v8, v8
	s_waitcnt lgkmcnt(2)
	v_mfma_f32_32x32x16_bf16 v[50:65], v[80:83], v[140:143], v[50:65]
	v_exp_f32_e32 v24, v24
	v_exp_f32_e32 v9, v9
	v_exp_f32_e32 v25, v25
	s_waitcnt lgkmcnt(1)
	v_mfma_f32_32x32x16_bf16 v[34:49], v[68:71], v[144:147], v[34:49]
	ds_read_b128 v[76:79], v67 offset:21632
	ds_read_b128 v[80:83], v67 offset:28288
	s_nop 0
	v_exp_f32_e32 v10, v10
	s_waitcnt lgkmcnt(2)
	v_mfma_f32_32x32x16_bf16 v[50:65], v[72:75], v[144:147], v[50:65]
	v_exp_f32_e32 v26, v26
	v_exp_f32_e32 v11, v11
	v_exp_f32_e32 v27, v27
	s_waitcnt lgkmcnt(1)
	v_mfma_f32_32x32x16_bf16 v[34:49], v[76:79], v[148:151], v[34:49]
	ds_read_b128 v[68:71], v67 offset:21664
	ds_read_b128 v[72:75], v67 offset:28320
	s_waitcnt lgkmcnt(2)
	v_mfma_f32_32x32x16_bf16 v[50:65], v[80:83], v[148:151], v[50:65]
	v_exp_f32_e32 v12, v12
	v_exp_f32_e32 v28, v28
	v_exp_f32_e32 v13, v13
	v_exp_f32_e32 v29, v29
	v_exp_f32_e32 v14, v14
	v_exp_f32_e32 v30, v30
	v_exp_f32_e32 v15, v15
	v_exp_f32_e32 v31, v31
	v_add_f32_e32 v67, 0, v2
	v_add_f32_e32 v67, v18, v67
	v_add_f32_e32 v67, v67, v3
	v_add_f32_e32 v67, v19, v67
	v_add_f32_e32 v67, v67, v4
	v_add_f32_e32 v67, v20, v67
	v_add_f32_e32 v67, v67, v5
	v_add_f32_e32 v67, v21, v67
	v_add_f32_e32 v67, v67, v6
	v_add_f32_e32 v67, v22, v67
	v_add_f32_e32 v67, v67, v7
	v_add_f32_e32 v67, v23, v67
	v_add_f32_e32 v67, v67, v8
	v_add_f32_e32 v67, v24, v67
	v_add_f32_e32 v67, v67, v9
	v_add_f32_e32 v67, v25, v67
	v_add_f32_e32 v67, v67, v10
	v_add_f32_e32 v67, v26, v67
	v_add_f32_e32 v67, v67, v11
	v_add_f32_e32 v67, v27, v67
	v_add_f32_e32 v67, v67, v12
	v_add_f32_e32 v67, v28, v67
	v_add_f32_e32 v67, v67, v13
	v_add_f32_e32 v67, v29, v67
	v_exp_f32_e32 v16, v16
	s_waitcnt lgkmcnt(1)
; #define LAS __attribute__((address_space(3)))
; __device__ __forceinline__ void att_qk_exp(const LAS char* kb, const bf16x8 (&qf)[6], float nm, fa::f32x16& n0, fa::f32x16& n1, fa::f32x16& p0, fa::f32x16& p1, float& lsum, bf16x8 (&pf)[4]) {
;     const fa::f32x16 zero = {0.f, 0.f, 0.f, 0.f, 0.f, 0.f, 0.f, 0.f, 0.f, 0.f, 0.f, 0.f, 0.f, 0.f, 0.f, 0.f};
;     bf16x8 kc0 = *(const LAS bf16x8*)kb, kc1 = *(const LAS bf16x8*)(kb + 32 * fa::KP_A);
;     float ps = 0.f, ps2 = 0.f;
; #pragma unroll
;     for (int st = 0; st < 6; ++st) {
;         bf16x8 kn0 = kc0, kn1 = kc1;
;         if (st < 5) { kn0 = *(const LAS bf16x8*)(kb + 32 * (st + 1)); kn1 = *(const LAS bf16x8*)(kb + 32 * fa::KP_A + 32 * (st + 1)); }
;         n0 = __builtin_amdgcn_mfma_f32_32x32x16_bf16(kc0, qf[st], st == 0 ? zero : n0, 0, 0, 0);
;         n1 = __builtin_amdgcn_mfma_f32_32x32x16_bf16(kc1, qf[st], st == 0 ? zero : n1, 0, 0, 0);
;         constexpr int lo[7] = {0, 2, 6, 8, 10, 14, 16};
; #pragma unroll
;         for (int r = lo[st]; r < lo[st + 1]; ++r) {
;             p0[r] = __builtin_amdgcn_exp2f(vadd1(p0[r], nm)); p1[r] = __builtin_amdgcn_exp2f(vadd1(p1[r], nm));
;             ps += p0[r]; ps += p1[r]; }
;         kc0 = kn0; kc1 = kn1;
;         __builtin_amdgcn_sched_barrier(0);
;     }
;     lsum += ps + ps2;
;     pf[0] = fa::pack_p(p0, 0); pf[1] = fa::pack_p(p0, 8); pf[2] = fa::pack_p(p1, 0); pf[3] = fa::pack_p(p1, 8);
; }
; __device__ __forceinline__ void att_exp_pack(fa::f32x16& p0, fa::f32x16& p1, float nm, float& lsum, bf16x8 (&pf)[4]) {
;     float ps = 0.f, ps2 = 0.f;
; #pragma unroll
;     for (int r = 0; r < 16; ++r) { p0[r] = __builtin_amdgcn_exp2f(vadd1(p0[r], nm)); p1[r] = __builtin_amdgcn_exp2f(vadd1(p1[r], nm)); ps += p0[r]; ps += p1[r]; }
;     lsum += ps + ps2;
;     pf[0] = fa::pack_p(p0, 0); pf[1] = fa::pack_p(p0, 8); pf[2] = fa::pack_p(p1, 0); pf[3] = fa::pack_p(p1, 8);
; }
; __device__ __forceinline__ float att_pv_max(fa::f32x16& o0, fa::f32x16& o1, const LAS char* vb, const bf16x8 (&pf)[4], const fa::f32x16& n0, const fa::f32x16& n1) {
;     using namespace fa;
;     float ta = n0[0], tb = n1[0];
;     s16x4 a0 = vtr(vb), a1 = vtr(vb + 512), b0 = vtr(vb + 4096), b1 = vtr(vb + 4096 + 512);
; #pragma unroll
;     for (int ks = 0; ks < 4; ++ks) {
;         s16x4 na0 = a0, na1 = a1, nb0 = b0, nb1 = b1;
	v_mfma_f32_32x32x16_bf16 v[34:49], v[68:71], v[152:155], v[34:49]
	v_add_f32_e32 v67, v67, v14
	v_exp_f32_e32 v32, v32
	v_add_f32_e32 v67, v30, v67
	v_exp_f32_e32 v17, v17
	v_add_f32_e32 v67, v67, v15
	s_waitcnt lgkmcnt(0)
	v_mfma_f32_32x32x16_bf16 v[50:65], v[72:75], v[152:155], v[50:65]
	v_exp_f32_e32 v33, v33
	v_add_f32_e32 v67, v31, v67
	v_add_f32_e32 v67, v67, v16
	v_add_f32_e32 v67, v32, v67
	v_add_f32_e32 v67, v67, v17
	v_add_f32_e32 v67, v33, v67
	v_add_u32_e32 v193, s8, v189
	v_cvt_pk_bf16_f32 v68, v2, v3
	v_cvt_pk_bf16_f32 v69, v4, v5
	v_cvt_pk_bf16_f32 v70, v6, v7
	v_cvt_pk_bf16_f32 v71, v8, v9
	v_cvt_pk_bf16_f32 v72, v10, v11
	v_cvt_pk_bf16_f32 v73, v12, v13
	v_cvt_pk_bf16_f32 v74, v14, v15
	v_cvt_pk_bf16_f32 v75, v16, v17
	v_cvt_pk_bf16_f32 v76, v18, v19
	v_cvt_pk_bf16_f32 v77, v20, v21
	v_cvt_pk_bf16_f32 v78, v22, v23
	v_cvt_pk_bf16_f32 v79, v24, v25
	v_cvt_pk_bf16_f32 v196, v26, v27
	v_cvt_pk_bf16_f32 v197, v28, v29
	v_cvt_pk_bf16_f32 v198, v30, v31
	v_cvt_pk_bf16_f32 v199, v32, v33
	ds_read_b64_tr_b16 v[80:81], v193 offset:13312
	ds_read_b64_tr_b16 v[82:83], v193 offset:13824
	ds_read_b64_tr_b16 v[84:85], v193 offset:14336
	ds_read_b64_tr_b16 v[86:87], v193 offset:14848
	s_waitcnt lgkmcnt(2)
	v_mfma_f32_32x32x16_bf16 v[114:129], v[80:83], v[68:71], v[114:129]
	ds_read_b64_tr_b16 v[80:81], v193 offset:17408
	ds_read_b64_tr_b16 v[82:83], v193 offset:17920
	ds_read_b64_tr_b16 v[88:89], v193 offset:18432
	ds_read_b64_tr_b16 v[90:91], v193 offset:18944
	v_add_f32_e32 v67, 0, v67
	v_add_f32_e32 v192, v66, v67
	s_waitcnt lgkmcnt(2)
	v_mfma_f32_32x32x16_bf16 v[98:113], v[80:83], v[68:71], v[98:113]
	s_waitcnt lgkmcnt(0)
	v_mfma_f32_32x32x16_bf16 v[98:113], v[88:91], v[72:75], v[98:113]
	ds_read_b64_tr_b16 v[66:67], v193 offset:15360
	ds_read_b64_tr_b16 v[68:69], v193 offset:15872
	ds_read_b64_tr_b16 v[80:81], v193 offset:19456
	ds_read_b64_tr_b16 v[82:83], v193 offset:19968
	v_mfma_f32_32x32x16_bf16 v[114:129], v[84:87], v[72:75], v[114:129]
	s_waitcnt lgkmcnt(0)
	v_mfma_f32_32x32x16_bf16 v[98:113], v[80:83], v[76:79], v[98:113]
	ds_read_b64_tr_b16 v[84:85], v193 offset:16384
	ds_read_b64_tr_b16 v[86:87], v193 offset:16896
	ds_read_b64_tr_b16 v[200:201], v193 offset:20480
	ds_read_b64_tr_b16 v[202:203], v193 offset:20992
	v_mfma_f32_32x32x16_bf16 v[114:129], v[66:69], v[76:79], v[114:129]
	v_max_f32_e32 v66, v51, v51
	v_max_f32_e32 v67, v50, v50
	v_max_f32_e32 v66, v67, v66
	v_max3_f32 v66, v66, v52, v53
	v_max3_f32 v66, v66, v54, v55
	v_max3_f32 v66, v66, v56, v57
	v_max3_f32 v82, v66, v58, v59
	v_max3_f32 v66, v82, v60, v61
	v_max3_f32 v82, v34, v35, v36
	v_max3_f32 v82, v82, v37, v38
	v_max3_f32 v82, v82, v39, v40
	v_max3_f32 v82, v82, v41, v42
	s_waitcnt lgkmcnt(2)
	v_mfma_f32_32x32x16_bf16 v[114:129], v[84:87], v[196:199], v[114:129]
	v_max3_f32 v67, v82, v43, v44
	v_max3_f32 v82, v67, v45, v46
	v_max3_f32 v83, v66, v62, v63
	s_waitcnt lgkmcnt(0)
	v_mfma_f32_32x32x16_bf16 v[98:113], v[200:203], v[196:199], v[98:113]
	v_max3_f32 v82, v82, v47, v48
	v_max3_f32 v83, v83, v64, v65
	v_max3_f32 v82, v82, v49, v83
	v_cmp_lt_f32_e32 vcc, 0x41000000, v82
	s_cbranch_vccz .LBB0_1033
	v_and_b32_e32 v84, 64, v1
	v_xor_b32_e32 v83, 32, v1
	v_add_u32_e32 v84, 64, v84
	v_cmp_lt_i32_e32 vcc, v83, v84
	s_nop 1
	v_cndmask_b32_e32 v83, v1, v83, vcc
	v_lshlrev_b32_e32 v83, 2, v83
	ds_bpermute_b32 v83, v83, v82
	v_max_f32_e32 v82, v82, v82
	s_waitcnt lgkmcnt(0)
	v_max_f32_e32 v83, v83, v83
	v_max_f32_e32 v82, v82, v83
	v_max_f32_e32 v83, 0, v82
	v_exp_f32_e64 v82, -v83
	v_add_f32_e32 v190, v190, v83
	v_mul_f32_e32 v192, v192, v82
	v_pk_mul_f32 v[128:129], v[128:129], v[82:83] op_sel_hi:[1,0]
	v_pk_mul_f32 v[126:127], v[126:127], v[82:83] op_sel_hi:[1,0]
	v_pk_mul_f32 v[124:125], v[124:125], v[82:83] op_sel_hi:[1,0]
	v_pk_mul_f32 v[122:123], v[122:123], v[82:83] op_sel_hi:[1,0]
	v_pk_mul_f32 v[120:121], v[120:121], v[82:83] op_sel_hi:[1,0]
	v_pk_mul_f32 v[118:119], v[118:119], v[82:83] op_sel_hi:[1,0]
	v_pk_mul_f32 v[116:117], v[116:117], v[82:83] op_sel_hi:[1,0]
	v_pk_mul_f32 v[114:115], v[114:115], v[82:83] op_sel_hi:[1,0]
	v_pk_mul_f32 v[112:113], v[112:113], v[82:83] op_sel_hi:[1,0]
	v_pk_mul_f32 v[110:111], v[110:111], v[82:83] op_sel_hi:[1,0]
	v_pk_mul_f32 v[108:109], v[108:109], v[82:83] op_sel_hi:[1,0]
	v_pk_mul_f32 v[106:107], v[106:107], v[82:83] op_sel_hi:[1,0]
	v_pk_mul_f32 v[104:105], v[104:105], v[82:83] op_sel_hi:[1,0]
	v_pk_mul_f32 v[102:103], v[102:103], v[82:83] op_sel_hi:[1,0]
	v_pk_mul_f32 v[100:101], v[100:101], v[82:83] op_sel_hi:[1,0]
	v_pk_mul_f32 v[98:99], v[98:99], v[82:83] op_sel_hi:[1,0]
	v_sub_f32_e32 v34, v34, v83
	v_sub_f32_e32 v35, v35, v83
	v_sub_f32_e32 v36, v36, v83
	v_sub_f32_e32 v37, v37, v83
	v_sub_f32_e32 v38, v38, v83
	v_sub_f32_e32 v39, v39, v83
	v_sub_f32_e32 v40, v40, v83
	v_sub_f32_e32 v41, v41, v83
	v_sub_f32_e32 v42, v42, v83
	v_sub_f32_e32 v43, v43, v83
	v_sub_f32_e32 v44, v44, v83
	v_sub_f32_e32 v45, v45, v83
	v_sub_f32_e32 v46, v46, v83
	v_sub_f32_e32 v47, v47, v83
	v_sub_f32_e32 v48, v48, v83
	v_sub_f32_e32 v49, v49, v83
	v_sub_f32_e32 v50, v50, v83
	v_sub_f32_e32 v51, v51, v83
	v_sub_f32_e32 v52, v52, v83
	v_sub_f32_e32 v53, v53, v83
	v_sub_f32_e32 v54, v54, v83
	v_sub_f32_e32 v55, v55, v83
	v_sub_f32_e32 v56, v56, v83
	v_sub_f32_e32 v57, v57, v83
	v_sub_f32_e32 v58, v58, v83
	v_sub_f32_e32 v59, v59, v83
	v_sub_f32_e32 v60, v60, v83
	v_sub_f32_e32 v61, v61, v83
	v_sub_f32_e32 v62, v62, v83
	v_sub_f32_e32 v63, v63, v83
	v_sub_f32_e32 v64, v64, v83
	v_sub_f32_e32 v65, v65, v83
	v_sub_f32_e32 v226, v226, v83
	v_sub_f32_e32 v227, v227, v83
	v_sub_f32_e32 v228, v228, v83
	v_sub_f32_e32 v229, v229, v83
	v_sub_f32_e32 v230, v230, v83
	v_sub_f32_e32 v231, v231, v83
	v_sub_f32_e32 v232, v232, v83
	v_sub_f32_e32 v233, v233, v83
	v_sub_f32_e32 v234, v234, v83
	v_sub_f32_e32 v235, v235, v83
	v_sub_f32_e32 v236, v236, v83
	v_sub_f32_e32 v237, v237, v83
	v_sub_f32_e32 v238, v238, v83
	v_sub_f32_e32 v239, v239, v83
	v_sub_f32_e32 v240, v240, v83
	v_sub_f32_e32 v241, v241, v83
; #define LAS __attribute__((address_space(3)))
; __device__ __forceinline__ s16x4 vtr(const LAS char* p) { return __builtin_bit_cast(s16x4, __builtin_amdgcn_ds_read_tr16_b64_v4i16((LAS s16x4*)p)); }
; __device__ __forceinline__ bf16x8 pack_p(const f32x16& p, int base) { u32x4 w; w.x = pk2(p[base], p[base + 1]); w.y = pk2(p[base + 2], p[base + 3]); w.z = pk2(p[base + 4], p[base + 5]); w.w = pk2(p[base + 6], p[base + 7]); return __builtin_bit_cast(bf16x8, w); }
; __device__ __forceinline__ float vadd1(float a, float b) { float r; asm("v_add_f32 %0, %1, %2" : "=v"(r) : "v"(a), "v"(b)); return r; }
; __device__ __forceinline__ void pv_tile(f32x16& o0, f32x16& o1, const LAS char* vb, const bf16x8 (&pf)[4]) {
; #pragma unroll
;     for (int ks = 0; ks < 4; ++ks) {
;         const s16x4 a0 = vtr(vb + ks * 1024), a1 = vtr(vb + ks * 1024 + 512), b0 = vtr(vb + 4096 + ks * 1024), b1 = vtr(vb + 4096 + ks * 1024 + 512);
;         const bf16x8 v0 = (bf16x8){a0[0], a0[1], a0[2], a0[3], a1[0], a1[1], a1[2], a1[3]}, v1 = (bf16x8){b0[0], b0[1], b0[2], b0[3], b1[0], b1[1], b1[2], b1[3]};
;         o0 = __builtin_amdgcn_mfma_f32_32x32x16_bf16(v0, pf[ks], o0, 0, 0, 0);
;         o1 = __builtin_amdgcn_mfma_f32_32x32x16_bf16(v1, pf[ks], o1, 0, 0, 0);
;     }
; }
; __device__ __forceinline__ void att_exp_pack(fa::f32x16& p0, fa::f32x16& p1, float nm, float& lsum, bf16x8 (&pf)[4]) {
;     float ps = 0.f, ps2 = 0.f;
; #pragma unroll
;     for (int r = 0; r < 16; ++r) { p0[r] = __builtin_amdgcn_exp2f(vadd1(p0[r], nm)); p1[r] = __builtin_amdgcn_exp2f(vadd1(p1[r], nm)); ps += p0[r]; ps += p1[r]; }
;     lsum += ps + ps2;
;     pf[0] = fa::pack_p(p0, 0); pf[1] = fa::pack_p(p0, 8); pf[2] = fa::pack_p(p1, 0); pf[3] = fa::pack_p(p1, 8);
; }
.LBB0_1033:
	s_mov_b64 s[8:9], -1
	s_and_b64 vcc, exec, s[10:11]
	v_xor_b32_e32 v194, 0x80000000, v190
	s_barrier
	s_cbranch_vccz .LBB0_1035
	s_nop 0
	v_exp_f32_e32 v82, v34
	v_exp_f32_e32 v83, v50
	v_exp_f32_e32 v85, v35
	v_exp_f32_e32 v86, v51
	v_add_f32_e32 v84, 0, v82
	v_exp_f32_e32 v87, v36
	v_add_f32_e32 v84, v83, v84
	v_exp_f32_e32 v88, v52
	v_add_f32_e32 v84, v84, v85
	v_exp_f32_e32 v89, v37
	v_add_f32_e32 v84, v86, v84
	v_exp_f32_e32 v90, v53
	v_add_f32_e32 v84, v84, v87
	v_exp_f32_e32 v91, v38
	v_add_f32_e32 v84, v88, v84
	v_exp_f32_e32 v92, v54
	v_add_f32_e32 v84, v84, v89
	v_exp_f32_e32 v93, v39
	v_add_f32_e32 v84, v90, v84
	v_exp_f32_e32 v94, v55
	v_add_f32_e32 v84, v84, v91
	v_exp_f32_e32 v95, v40
	v_add_f32_e32 v84, v92, v84
	v_exp_f32_e32 v96, v56
	v_add_f32_e32 v84, v84, v93
	v_exp_f32_e32 v97, v41
	v_add_f32_e32 v84, v94, v84
	v_exp_f32_e32 v66, v57
	v_add_f32_e32 v84, v84, v95
	v_exp_f32_e32 v67, v42
	v_add_f32_e32 v84, v96, v84
	v_exp_f32_e32 v68, v58
	v_add_f32_e32 v84, v84, v97
	v_exp_f32_e32 v69, v43
	v_add_f32_e32 v84, v66, v84
	v_exp_f32_e32 v70, v59
	v_add_f32_e32 v84, v84, v67
	v_exp_f32_e32 v71, v44
	v_add_f32_e32 v84, v68, v84
	v_exp_f32_e32 v72, v60
	v_add_f32_e32 v84, v84, v69
	v_exp_f32_e32 v73, v45
	v_add_f32_e32 v84, v70, v84
	v_exp_f32_e32 v74, v61
	v_add_f32_e32 v84, v84, v71
	v_exp_f32_e32 v75, v46
	v_add_f32_e32 v84, v72, v84
	v_exp_f32_e32 v76, v62
	v_add_f32_e32 v84, v84, v73
	v_exp_f32_e32 v77, v47
	v_add_f32_e32 v84, v74, v84
	v_exp_f32_e32 v78, v63
	v_add_f32_e32 v84, v84, v75
	v_exp_f32_e32 v79, v48
	v_add_f32_e32 v84, v76, v84
	v_exp_f32_e32 v80, v64
	v_add_f32_e32 v84, v84, v77
	v_exp_f32_e32 v81, v49
	v_add_f32_e32 v84, v78, v84
	v_add_f32_e32 v84, v84, v79
	v_exp_f32_e32 v204, v65
	v_add_f32_e32 v84, v80, v84
	v_add_f32_e32 v84, v84, v81
	v_cvt_pk_bf16_f32 v196, v82, v85
	v_add_f32_e32 v195, v204, v84
	v_cvt_pk_bf16_f32 v197, v87, v89
	v_cvt_pk_bf16_f32 v198, v91, v93
	v_cvt_pk_bf16_f32 v199, v95, v97
	v_cvt_pk_bf16_f32 v200, v67, v69
	v_cvt_pk_bf16_f32 v201, v71, v73
	v_cvt_pk_bf16_f32 v202, v75, v77
	v_cvt_pk_bf16_f32 v203, v79, v81
	v_cvt_pk_bf16_f32 v214, v83, v86
	v_cvt_pk_bf16_f32 v215, v88, v90
	v_cvt_pk_bf16_f32 v216, v92, v94
	v_cvt_pk_bf16_f32 v217, v96, v66
	v_cvt_pk_bf16_f32 v218, v68, v70
	v_cvt_pk_bf16_f32 v219, v72, v74
	v_cvt_pk_bf16_f32 v220, v76, v78
	v_cvt_pk_bf16_f32 v221, v80, v204
	ds_read_b64_tr_b16 v[82:83], v193 offset:34816
	ds_read_b64_tr_b16 v[84:85], v193 offset:35328
	ds_read_b64_tr_b16 v[222:223], v193 offset:38912
	ds_read_b64_tr_b16 v[224:225], v193 offset:39424
	s_waitcnt lgkmcnt(2)
	v_mfma_f32_32x32x16_bf16 v[114:129], v[82:85], v[196:199], v[114:129]
	s_mov_b64 s[8:9], 0
	s_waitcnt lgkmcnt(0)
	v_mfma_f32_32x32x16_bf16 v[98:113], v[222:225], v[196:199], v[98:113]
	ds_read_b64_tr_b16 v[196:197], v193 offset:35840
	ds_read_b64_tr_b16 v[198:199], v193 offset:36352
	ds_read_b64_tr_b16 v[222:223], v193 offset:39936
	ds_read_b64_tr_b16 v[224:225], v193 offset:40448
	s_waitcnt lgkmcnt(2)
	v_mfma_f32_32x32x16_bf16 v[114:129], v[196:199], v[200:203], v[114:129]
	s_waitcnt lgkmcnt(0)
	v_mfma_f32_32x32x16_bf16 v[98:113], v[222:225], v[200:203], v[98:113]
	ds_read_b64_tr_b16 v[196:197], v193 offset:36864
	ds_read_b64_tr_b16 v[198:199], v193 offset:37376
	ds_read_b64_tr_b16 v[200:201], v193 offset:40960
	ds_read_b64_tr_b16 v[202:203], v193 offset:41472
	s_waitcnt lgkmcnt(2)
	v_mfma_f32_32x32x16_bf16 v[114:129], v[196:199], v[214:217], v[114:129]
	s_waitcnt lgkmcnt(0)
	v_mfma_f32_32x32x16_bf16 v[98:113], v[200:203], v[214:217], v[98:113]
	ds_read_b64_tr_b16 v[196:197], v193 offset:37888
	ds_read_b64_tr_b16 v[198:199], v193 offset:38400
	ds_read_b64_tr_b16 v[200:201], v193 offset:41984
	ds_read_b64_tr_b16 v[202:203], v193 offset:42496
	s_waitcnt lgkmcnt(2)
	v_mfma_f32_32x32x16_bf16 v[114:129], v[196:199], v[218:221], v[114:129]
	s_waitcnt lgkmcnt(0)
	v_mfma_f32_32x32x16_bf16 v[98:113], v[200:203], v[218:221], v[98:113]
; #define LAS __attribute__((address_space(3)))
; __device__ __forceinline__ void att_qk_exp(const LAS char* kb, const bf16x8 (&qf)[6], float nm, fa::f32x16& n0, fa::f32x16& n1, fa::f32x16& p0, fa::f32x16& p1, float& lsum, bf16x8 (&pf)[4]) {
;     const fa::f32x16 zero = {0.f, 0.f, 0.f, 0.f, 0.f, 0.f, 0.f, 0.f, 0.f, 0.f, 0.f, 0.f, 0.f, 0.f, 0.f, 0.f};
;     bf16x8 kc0 = *(const LAS bf16x8*)kb, kc1 = *(const LAS bf16x8*)(kb + 32 * fa::KP_A);
;     float ps = 0.f, ps2 = 0.f;
; #pragma unroll
;     for (int st = 0; st < 6; ++st) {
;         bf16x8 kn0 = kc0, kn1 = kc1;
;         if (st < 5) { kn0 = *(const LAS bf16x8*)(kb + 32 * (st + 1)); kn1 = *(const LAS bf16x8*)(kb + 32 * fa::KP_A + 32 * (st + 1)); }
;         n0 = __builtin_amdgcn_mfma_f32_32x32x16_bf16(kc0, qf[st], st == 0 ? zero : n0, 0, 0, 0);
;         n1 = __builtin_amdgcn_mfma_f32_32x32x16_bf16(kc1, qf[st], st == 0 ? zero : n1, 0, 0, 0);
;         constexpr int lo[7] = {0, 2, 6, 8, 10, 14, 16};
; #pragma unroll
;         for (int r = lo[st]; r < lo[st + 1]; ++r) {
;             p0[r] = __builtin_amdgcn_exp2f(vadd1(p0[r], nm)); p1[r] = __builtin_amdgcn_exp2f(vadd1(p1[r], nm));
;             ps += p0[r]; ps += p1[r]; }
;         kc0 = kn0; kc1 = kn1;
;         __builtin_amdgcn_sched_barrier(0);
;     }
;     lsum += ps + ps2;
;     pf[0] = fa::pack_p(p0, 0); pf[1] = fa::pack_p(p0, 8); pf[2] = fa::pack_p(p1, 0); pf[3] = fa::pack_p(p1, 8);
; }
; __device__ __forceinline__ void att_exp_pack(fa::f32x16& p0, fa::f32x16& p1, float nm, float& lsum, bf16x8 (&pf)[4]) {
;     float ps = 0.f, ps2 = 0.f;
; #pragma unroll
;     for (int r = 0; r < 16; ++r) { p0[r] = __builtin_amdgcn_exp2f(vadd1(p0[r], nm)); p1[r] = __builtin_amdgcn_exp2f(vadd1(p1[r], nm)); ps += p0[r]; ps += p1[r]; }
;     lsum += ps + ps2;
;     pf[0] = fa::pack_p(p0, 0); pf[1] = fa::pack_p(p0, 8); pf[2] = fa::pack_p(p1, 0); pf[3] = fa::pack_p(p1, 8);
; }
; __device__ __forceinline__ float att_pv_max(fa::f32x16& o0, fa::f32x16& o1, const LAS char* vb, const bf16x8 (&pf)[4], const fa::f32x16& n0, const fa::f32x16& n1) {
;     using namespace fa;
;     float ta = n0[0], tb = n1[0];
;     s16x4 a0 = vtr(vb), a1 = vtr(vb + 512), b0 = vtr(vb + 4096), b1 = vtr(vb + 4096 + 512);
; #pragma unroll
;     for (int ks = 0; ks < 4; ++ks) {
;         s16x4 na0 = a0, na1 = a1, nb0 = b0, nb1 = b1;
.LBB0_1035:
	s_andn2_b64 vcc, exec, s[8:9]
	s_cbranch_vccnz .LBB0_1037
	s_nop 7
	v_add_u32_e32 v66, s18, v188
	ds_read_b128 v[2:5], v66
	ds_read_b128 v[18:21], v66 offset:6656
	ds_read_b128 v[82:85], v66 offset:32
	ds_read_b128 v[86:89], v66 offset:6688
	v_exp_f32_e32 v67, v34
	v_exp_f32_e32 v68, v50
	s_waitcnt lgkmcnt(3)
	v_mfma_f32_32x32x16_bf16 v[2:17], v[2:5], v[132:135], v[226:241]
	v_exp_f32_e32 v69, v35
	v_exp_f32_e32 v70, v51
	s_waitcnt lgkmcnt(2)
	v_mfma_f32_32x32x16_bf16 v[18:33], v[18:21], v[132:135], v[226:241]
	s_waitcnt lgkmcnt(1)
	v_mfma_f32_32x32x16_bf16 v[2:17], v[82:85], v[136:139], v[2:17]
	v_exp_f32_e32 v71, v36
	ds_read_b128 v[90:93], v66 offset:64
	ds_read_b128 v[94:97], v66 offset:6720
	v_exp_f32_e32 v72, v52
	s_nop 0
	v_exp_f32_e32 v82, v37
	s_waitcnt lgkmcnt(2)
	v_mfma_f32_32x32x16_bf16 v[18:33], v[86:89], v[136:139], v[18:33]
	v_exp_f32_e32 v83, v53
	s_nop 0
	v_exp_f32_e32 v84, v38
	s_nop 0
	v_exp_f32_e32 v85, v54
	s_nop 0
	v_exp_f32_e32 v73, v39
	s_nop 0
	v_exp_f32_e32 v74, v55
	s_waitcnt lgkmcnt(1)
	v_mfma_f32_32x32x16_bf16 v[2:17], v[90:93], v[140:143], v[2:17]
	ds_read_b128 v[34:37], v66 offset:96
	ds_read_b128 v[50:53], v66 offset:6752
	v_exp_f32_e32 v86, v40
	s_nop 0
	v_exp_f32_e32 v87, v56
	s_waitcnt lgkmcnt(2)
	v_mfma_f32_32x32x16_bf16 v[18:33], v[94:97], v[140:143], v[18:33]
	v_exp_f32_e32 v88, v41
	s_nop 0
	v_exp_f32_e32 v89, v57
	s_waitcnt lgkmcnt(1)
	v_mfma_f32_32x32x16_bf16 v[2:17], v[34:37], v[144:147], v[2:17]
	ds_read_b128 v[38:41], v66 offset:128
	ds_read_b128 v[54:57], v66 offset:6784
	s_nop 0
	v_exp_f32_e32 v42, v42
	s_nop 0
	v_exp_f32_e32 v58, v58
	s_waitcnt lgkmcnt(2)
	v_mfma_f32_32x32x16_bf16 v[18:33], v[50:53], v[144:147], v[18:33]
	s_nop 0
	v_exp_f32_e32 v43, v43
	s_nop 0
	v_exp_f32_e32 v59, v59
	s_waitcnt lgkmcnt(1)
	v_mfma_f32_32x32x16_bf16 v[2:17], v[38:41], v[148:151], v[2:17]
	ds_read_b128 v[34:37], v66 offset:160
	ds_read_b128 v[50:53], v66 offset:6816
	s_nop 0
	v_exp_f32_e32 v39, v45
	s_waitcnt lgkmcnt(2)
	v_mfma_f32_32x32x16_bf16 v[18:33], v[54:57], v[148:151], v[18:33]
	v_exp_f32_e32 v61, v61
	v_exp_f32_e32 v44, v44
	v_exp_f32_e32 v40, v46
	v_exp_f32_e32 v60, v60
	v_exp_f32_e32 v62, v62
	s_nop 0
	v_exp_f32_e32 v41, v47
	s_nop 0
	v_exp_f32_e32 v63, v63
	s_waitcnt lgkmcnt(1)
	v_mfma_f32_32x32x16_bf16 v[2:17], v[34:37], v[152:155], v[2:17]
	v_exp_f32_e32 v45, v48
	s_nop 0
	v_exp_f32_e32 v54, v64
	v_mov_b32_e32 v38, v49
	v_exp_f32_e32 v49, v65
	v_add_f32_e32 v34, 0, v67
	v_add_f32_e32 v34, v68, v34
	v_add_f32_e32 v34, v34, v69
	v_add_f32_e32 v34, v70, v34
	v_add_f32_e32 v34, v34, v71
	v_add_f32_e32 v34, v72, v34
	v_add_f32_e32 v34, v34, v82
	v_add_f32_e32 v34, v83, v34
	v_add_f32_e32 v34, v34, v84
	v_add_f32_e32 v34, v85, v34
	v_add_f32_e32 v34, v34, v73
	v_add_f32_e32 v34, v74, v34
	v_add_f32_e32 v34, v34, v86
	v_add_f32_e32 v34, v87, v34
	v_add_f32_e32 v34, v34, v88
	v_add_f32_e32 v34, v89, v34
	v_add_f32_e32 v34, v34, v42
	v_add_f32_e32 v34, v58, v34
	v_add_f32_e32 v34, v34, v43
	v_add_f32_e32 v34, v59, v34
	v_add_f32_e32 v34, v34, v44
	v_add_f32_e32 v34, v60, v34
	v_add_f32_e32 v34, v34, v39
	v_add_f32_e32 v34, v61, v34
	s_waitcnt lgkmcnt(0)
	v_mfma_f32_32x32x16_bf16 v[18:33], v[50:53], v[152:155], v[18:33]
	v_add_f32_e32 v34, v34, v40
	v_add_f32_e32 v34, v62, v34
	v_exp_f32_e32 v46, v38
	v_add_f32_e32 v34, v34, v41
	v_add_f32_e32 v34, v63, v34
	v_add_f32_e32 v34, v34, v45
	v_add_f32_e32 v34, v54, v34
	v_add_f32_e32 v34, v34, v46
	v_add_f32_e32 v195, v49, v34
	v_cvt_pk_bf16_f32 v34, v67, v69
	v_cvt_pk_bf16_f32 v35, v71, v82
	v_cvt_pk_bf16_f32 v36, v84, v73
	v_cvt_pk_bf16_f32 v37, v86, v88
	v_cvt_pk_bf16_f32 v38, v42, v43
	v_cvt_pk_bf16_f32 v39, v44, v39
	v_cvt_pk_bf16_f32 v40, v40, v41
	v_cvt_pk_bf16_f32 v41, v45, v46
	v_cvt_pk_bf16_f32 v42, v68, v70
	v_cvt_pk_bf16_f32 v43, v72, v83
	v_cvt_pk_bf16_f32 v44, v85, v74
	v_cvt_pk_bf16_f32 v45, v87, v89
	v_cvt_pk_bf16_f32 v46, v58, v59
	v_cvt_pk_bf16_f32 v47, v60, v61
	v_cvt_pk_bf16_f32 v48, v62, v63
	v_cvt_pk_bf16_f32 v49, v54, v49
	ds_read_b64_tr_b16 v[50:51], v193 offset:34816
	ds_read_b64_tr_b16 v[52:53], v193 offset:35328
	ds_read_b64_tr_b16 v[54:55], v193 offset:35840
	ds_read_b64_tr_b16 v[56:57], v193 offset:36352
	s_waitcnt lgkmcnt(2)
	v_mfma_f32_32x32x16_bf16 v[114:129], v[50:53], v[34:37], v[114:129]
	ds_read_b64_tr_b16 v[50:51], v193 offset:38912
	ds_read_b64_tr_b16 v[52:53], v193 offset:39424
	ds_read_b64_tr_b16 v[58:59], v193 offset:39936
	ds_read_b64_tr_b16 v[60:61], v193 offset:40448
	s_waitcnt lgkmcnt(2)
	v_mfma_f32_32x32x16_bf16 v[98:113], v[50:53], v[34:37], v[98:113]
	ds_read_b64_tr_b16 v[34:35], v193 offset:36864
	ds_read_b64_tr_b16 v[36:37], v193 offset:37376
	ds_read_b64_tr_b16 v[50:51], v193 offset:40960
	ds_read_b64_tr_b16 v[52:53], v193 offset:41472
	v_mfma_f32_32x32x16_bf16 v[114:129], v[54:57], v[38:41], v[114:129]
	s_waitcnt lgkmcnt(4)
	v_mfma_f32_32x32x16_bf16 v[98:113], v[58:61], v[38:41], v[98:113]
	s_waitcnt lgkmcnt(2)
	v_mfma_f32_32x32x16_bf16 v[114:129], v[34:37], v[42:45], v[114:129]
	ds_read_b64_tr_b16 v[34:35], v193 offset:37888
	ds_read_b64_tr_b16 v[36:37], v193 offset:38400
	ds_read_b64_tr_b16 v[38:39], v193 offset:41984
	ds_read_b64_tr_b16 v[40:41], v193 offset:42496
	s_waitcnt lgkmcnt(4)
	v_mfma_f32_32x32x16_bf16 v[98:113], v[50:53], v[42:45], v[98:113]
	v_max_f32_e32 v42, v19, v19
	v_max_f32_e32 v43, v18, v18
	v_max_f32_e32 v42, v43, v42
	v_max3_f32 v42, v42, v20, v21
	s_waitcnt lgkmcnt(2)
	v_mfma_f32_32x32x16_bf16 v[114:129], v[34:37], v[46:49], v[114:129]
	v_max3_f32 v35, v2, v3, v4
	v_max3_f32 v42, v42, v22, v23
	v_max3_f32 v35, v35, v5, v6
	v_max3_f32 v42, v42, v24, v25
	v_max3_f32 v35, v35, v7, v8
	v_max3_f32 v34, v42, v26, v27
	v_max3_f32 v35, v35, v9, v10
	v_max3_f32 v34, v34, v28, v29
	v_max3_f32 v35, v35, v11, v12
	v_max3_f32 v35, v35, v13, v14
	v_max3_f32 v34, v34, v30, v31
	s_waitcnt lgkmcnt(0)
	v_mfma_f32_32x32x16_bf16 v[98:113], v[38:41], v[46:49], v[98:113]
	v_max3_f32 v35, v35, v15, v16
	v_max3_f32 v34, v34, v32, v33
	v_max3_f32 v191, v35, v17, v34

; #define ATT_LOAD(k0_, k1_, v_, tt) do { const char* kg_ = Kg + (size_t)(tt) * 12288; const char* vg_ = Vg + (size_t)(tt) * 8192; \
;             k0_ = *(const u32x4*)(kg_ + tid_ * 16); if (tid_ < 256) k1_ = *(const u32x4*)(kg_ + (tid_ + 512) * 16); v_ = *(const u32x4*)(vg_ + tid_ * 16); } while (0)
; #define ATT_WRITE(k0_, k1_, v_, bo) do { *(LAS u32x4*)(sm + (bo) + koff0) = k0_; if (tid_ < 256) *(LAS u32x4*)(sm + (bo) + koff1) = k1_; *(LAS u32x4*)(sm + (bo) + voff) = v_; } while (0)
; __device__ __forceinline__ void ph_attn_mfma(unsigned char* lds_, const bf16_t* Q, const bf16_t* Kb, const bf16_t* Vb, bf16_t* Z, int with_ctx, int u0, int ustep) { PH_IDS;
;     ...
;         const bool lat = u < 256; const int bh = lat ? (u >> 3) : (u - 256), qb = lat ? (u & 7) : 8;
;         const int ntile = lat ? 36 : 4;
;         const char* Kg = (const char*)(Kb + (size_t)bh * 2304 * 96); const char* Vg = (const char*)(Vb + (size_t)bh * 2304 * 64);
;         const bf16_t* Qg = Q + ((size_t)bh * 2304 + qb * 256 + wid * 32 + r32) * 96;
;         bf16x8 qf[6];
; #pragma unroll
;         for (int st = 0; st < 6; ++st) qf[st] = *(const bf16x8*)(Qg + 16 * st + 8 * hi);
;         f32x16 o0, o1;
; #pragma unroll
;         for (int r = 0; r < 16; ++r) { o0[r] = 0.f; o1[r] = 0.f; }
;         float mrun = 0.f, lsum = 0.f;
;         f32x16 negm;
; #pragma unroll
;         for (int r = 0; r < 16; ++r) negm[r] = 0.f;
;         u32x4 ka0, ka1, va, kb0, kb1, vb;
;     ...
;         ka1 = (u32x4){0u, 0u, 0u, 0u}; kb1 = ka1;
;         const int npair = ntile >> 1;
;         ATT_LOAD(ka0, ka1, va, 0); ATT_LOAD(kb0, kb1, vb, 1);
;         __syncthreads();
;         ATT_WRITE(ka0, ka1, va, 0); ATT_WRITE(kb0, kb1, vb, BUF_A);
;         if (npair > 1) { ATT_LOAD(ka0, ka1, va, 2); ATT_LOAD(kb0, kb1, vb, 3); }
;         __syncthreads();
.LBB0_2962:
	s_lshl_b32 s8, s89, 8
	s_and_b32 s54, s8, 0x700
	s_ashr_i32 s36, s89, 3
	v_lshl_add_u64 v[2:3], v[186:187], 0, s[54:55]
	v_mad_i64_i32 v[2:3], s[8:9], s36, v212, v[2:3]
	v_mad_u64_u32 v[4:5], s[8:9], v2, s77, v[190:191]
	v_mov_b32_e32 v2, v5
	v_mad_u64_u32 v[2:3], s[8:9], v3, s77, v[2:3]
	v_mov_b32_e32 v5, v2
	s_mul_i32 s26, s36, 0x6c000
	global_load_dwordx4 v[134:137], v[4:5], off
	global_load_dwordx4 v[138:141], v[4:5], off offset:32
	global_load_dwordx4 v[142:145], v[4:5], off offset:64
	global_load_dwordx4 v[146:149], v[4:5], off offset:96
	global_load_dwordx4 v[150:153], v[4:5], off offset:128
	global_load_dwordx4 v[154:157], v[4:5], off offset:160
	s_mul_hi_i32 s27, s36, 0x6c000
	s_add_u32 s8, s30, s26
	s_addc_u32 s9, s31, s27
	v_lshl_add_u64 v[2:3], s[8:9], 0, v[184:185]
	global_load_dwordx4 v[6:9], v[2:3], off
	v_mov_b32_e32 v132, v130
	v_mov_b32_e32 v133, v130
	v_mov_b32_e32 v131, v130
	v_mov_b64_e32 v[232:233], 0
	v_mov_b64_e32 v[234:235], 0
	v_mov_b64_e32 v[236:237], 0
	v_mov_b64_e32 v[238:239], 0
	v_mov_b64_e32 v[240:241], 0
	v_mov_b64_e32 v[242:243], 0
	v_mov_b64_e32 v[244:245], 0
	v_mov_b64_e32 v[246:247], 0
	s_waitcnt vmcnt(14)
	v_mov_b64_e32 v[160:161], v[132:133]
	v_mov_b64_e32 v[158:159], v[130:131]
	s_and_saveexec_b64 s[10:11], s[4:5]
	s_cbranch_execz .LBB0_2964
	v_lshl_add_u64 v[2:3], s[8:9], 0, v[192:193]
	global_load_dwordx4 v[158:161], v[2:3], off

; #define LAS __attribute__((address_space(3)))
; __device__ __forceinline__ bf16x8 pack_p(const f32x16& p, int base) { u32x4 w; w.x = pk2(p[base], p[base + 1]); w.y = pk2(p[base + 2], p[base + 3]); w.z = pk2(p[base + 4], p[base + 5]); w.w = pk2(p[base + 6], p[base + 7]); return __builtin_bit_cast(bf16x8, w); }
; __device__ __forceinline__ float vadd1(float a, float b) { float r; asm("v_add_f32 %0, %1, %2" : "=v"(r) : "v"(a), "v"(b)); return r; }
; __device__ __forceinline__ void att_shift(float tm, bool first, float& mrun, float& lsum, fa::f32x16& o0, fa::f32x16& o1) {
;     if (first || __any(tm > mrun + 8.f)) {
;         tm = fmaxf(tm, __shfl_xor(tm, 32));
;         const float dl = first ? 0.f : fmaxf(tm - mrun, 0.f), alpha = __builtin_amdgcn_exp2f(-dl);
;         mrun = first ? tm : mrun + dl; lsum *= alpha;
; #pragma unroll
;         for (int r = 0; r < 16; ++r) { o0[r] *= alpha; o1[r] *= alpha; }
;     }
; }
; __device__ __forceinline__ void att_qk_exp(const LAS char* kb, const bf16x8 (&qf)[6], float nm, fa::f32x16& n0, fa::f32x16& n1, fa::f32x16& p0, fa::f32x16& p1, float& lsum, bf16x8 (&pf)[4]) {
;     const fa::f32x16 zero = {0.f, 0.f, 0.f, 0.f, 0.f, 0.f, 0.f, 0.f, 0.f, 0.f, 0.f, 0.f, 0.f, 0.f, 0.f, 0.f};
;     bf16x8 kc0 = *(const LAS bf16x8*)kb, kc1 = *(const LAS bf16x8*)(kb + 32 * fa::KP_A);
;     float ps = 0.f, ps2 = 0.f;
; #pragma unroll
;     for (int st = 0; st < 6; ++st) {
;         bf16x8 kn0 = kc0, kn1 = kc1;
;         if (st < 5) { kn0 = *(const LAS bf16x8*)(kb + 32 * (st + 1)); kn1 = *(const LAS bf16x8*)(kb + 32 * fa::KP_A + 32 * (st + 1)); }
;         n0 = __builtin_amdgcn_mfma_f32_32x32x16_bf16(kc0, qf[st], st == 0 ? zero : n0, 0, 0, 0);
;         n1 = __builtin_amdgcn_mfma_f32_32x32x16_bf16(kc1, qf[st], st == 0 ? zero : n1, 0, 0, 0);
;         constexpr int lo[7] = {0, 2, 6, 8, 10, 14, 16};
; #pragma unroll
;         for (int r = lo[st]; r < lo[st + 1]; ++r) {
;             p0[r] = __builtin_amdgcn_exp2f(vadd1(p0[r], nm)); p1[r] = __builtin_amdgcn_exp2f(vadd1(p1[r], nm));
;             ps += p0[r]; ps += p1[r]; }
;         kc0 = kn0; kc1 = kn1;
;         __builtin_amdgcn_sched_barrier(0);
;     }
;     lsum += ps + ps2;
;     pf[0] = fa::pack_p(p0, 0); pf[1] = fa::pack_p(p0, 8); pf[2] = fa::pack_p(p1, 0); pf[3] = fa::pack_p(p1, 8);
; }
.LBB0_2987:
	s_cmp_eq_u32 s10, 0
	s_cselect_b64 s[14:15], -1, 0
	s_and_b64 vcc, exec, s[14:15]
	s_mov_b64 s[16:17], s[14:15]
	s_cbranch_vccnz .LBB0_2989
	v_add_f32_e32 v222, 0x41000000, v131
	v_cmp_lt_f32_e32 vcc, 0x41000000, v201
	s_cmp_lg_u64 vcc, 0
	s_cselect_b64 s[16:17], -1, 0
.LBB0_2989:
	s_andn2_b64 vcc, exec, s[16:17]
	s_cbranch_vccnz .LBB0_2991
	v_and_b32_e32 v35, 64, v1
	v_xor_b32_e32 v34, 32, v1
	v_add_u32_e32 v35, 64, v35
	v_cmp_lt_i32_e32 vcc, v34, v35
	v_max_f32_e32 v35, v201, v201
	s_nop 0
	v_cndmask_b32_e32 v34, v1, v34, vcc
	v_lshlrev_b32_e32 v34, 2, v34
	ds_bpermute_b32 v34, v34, v201
	s_waitcnt lgkmcnt(0)
	v_max_f32_e32 v34, v34, v34
	v_max_f32_e32 v35, v35, v34
	v_mov_b32_e32 v34, v35
	v_max_f32_e32 v36, 0, v34
	v_cndmask_b32_e64 v248, v36, v35, s[14:15]
	v_cndmask_b32_e64 v34, -v36, v213, s[14:15]
	v_exp_f32_e32 v34, v34
	v_add_f32_e32 v36, v131, v36
	v_cndmask_b32_e64 v131, v36, v35, s[14:15]
	v_add_f32_e32 v222, 0x41000000, v131
	v_mul_f32_e32 v98, v98, v34
	v_pk_mul_f32 v[96:97], v[96:97], v[34:35] op_sel_hi:[1,0]
	v_pk_mul_f32 v[94:95], v[94:95], v[34:35] op_sel_hi:[1,0]
	v_pk_mul_f32 v[92:93], v[92:93], v[34:35] op_sel_hi:[1,0]
	v_pk_mul_f32 v[90:91], v[90:91], v[34:35] op_sel_hi:[1,0]
	v_pk_mul_f32 v[88:89], v[88:89], v[34:35] op_sel_hi:[1,0]
	v_pk_mul_f32 v[86:87], v[86:87], v[34:35] op_sel_hi:[1,0]
	v_pk_mul_f32 v[84:85], v[84:85], v[34:35] op_sel_hi:[1,0]
	v_pk_mul_f32 v[82:83], v[82:83], v[34:35] op_sel_hi:[1,0]
	v_pk_mul_f32 v[80:81], v[80:81], v[34:35] op_sel_hi:[1,0]
	v_pk_mul_f32 v[78:79], v[78:79], v[34:35] op_sel_hi:[1,0]
	v_pk_mul_f32 v[76:77], v[76:77], v[34:35] op_sel_hi:[1,0]
	v_pk_mul_f32 v[74:75], v[74:75], v[34:35] op_sel_hi:[1,0]
	v_pk_mul_f32 v[72:73], v[72:73], v[34:35] op_sel_hi:[1,0]
	v_pk_mul_f32 v[70:71], v[70:71], v[34:35] op_sel_hi:[1,0]
	v_pk_mul_f32 v[68:69], v[68:69], v[34:35] op_sel_hi:[1,0]
	v_pk_mul_f32 v[66:67], v[66:67], v[34:35] op_sel_hi:[1,0]
	v_sub_f32_e32 v2, v2, v248
	v_sub_f32_e32 v3, v3, v248
	v_sub_f32_e32 v4, v4, v248
	v_sub_f32_e32 v5, v5, v248
	v_sub_f32_e32 v6, v6, v248
	v_sub_f32_e32 v7, v7, v248
	v_sub_f32_e32 v8, v8, v248
	v_sub_f32_e32 v9, v9, v248
	v_sub_f32_e32 v10, v10, v248
	v_sub_f32_e32 v11, v11, v248
	v_sub_f32_e32 v12, v12, v248
	v_sub_f32_e32 v13, v13, v248
	v_sub_f32_e32 v14, v14, v248
	v_sub_f32_e32 v15, v15, v248
	v_sub_f32_e32 v16, v16, v248
	v_sub_f32_e32 v17, v17, v248
	v_sub_f32_e32 v18, v18, v248
	v_sub_f32_e32 v19, v19, v248
	v_sub_f32_e32 v20, v20, v248
	v_sub_f32_e32 v21, v21, v248
	v_sub_f32_e32 v22, v22, v248
	v_sub_f32_e32 v23, v23, v248
	v_sub_f32_e32 v24, v24, v248
	v_sub_f32_e32 v25, v25, v248
	v_sub_f32_e32 v26, v26, v248
	v_sub_f32_e32 v27, v27, v248
	v_sub_f32_e32 v28, v28, v248
	v_sub_f32_e32 v29, v29, v248
	v_sub_f32_e32 v30, v30, v248
	v_sub_f32_e32 v31, v31, v248
	v_sub_f32_e32 v32, v32, v248
	v_sub_f32_e32 v33, v33, v248
	v_sub_f32_e32 v232, v232, v248
	v_sub_f32_e32 v233, v233, v248
	v_sub_f32_e32 v234, v234, v248
	v_sub_f32_e32 v235, v235, v248
	v_sub_f32_e32 v236, v236, v248
	v_sub_f32_e32 v237, v237, v248
	v_sub_f32_e32 v238, v238, v248
	v_sub_f32_e32 v239, v239, v248
	v_sub_f32_e32 v240, v240, v248
	v_sub_f32_e32 v241, v241, v248
	v_sub_f32_e32 v242, v242, v248
	v_sub_f32_e32 v243, v243, v248
	v_sub_f32_e32 v244, v244, v248
	v_sub_f32_e32 v245, v245, v248
	v_sub_f32_e32 v246, v246, v248
	v_sub_f32_e32 v247, v247, v248
.LBB0_2991:
	s_add_i32 s8, s8, 0
	v_add3_u32 v99, s8, v217, v188
	ds_read_b128 v[34:37], v99 offset:21504
	ds_read_b128 v[50:53], v99 offset:28160
	ds_read_b128 v[100:103], v99 offset:21536
	s_waitcnt lgkmcnt(1)
	v_mfma_f32_32x32x16_bf16 v[50:65], v[50:53], v[134:137], v[232:247]
	ds_read_b128 v[104:107], v99 offset:28192
	v_exp_f32_e32 v2, v2
	v_exp_f32_e32 v18, v18
	v_exp_f32_e32 v3, v3
	v_mfma_f32_32x32x16_bf16 v[34:49], v[34:37], v[134:137], v[232:247]
	v_exp_f32_e32 v19, v19
	s_waitcnt lgkmcnt(1)
	v_mfma_f32_32x32x16_bf16 v[34:49], v[100:103], v[138:141], v[34:49]
	ds_read_b128 v[108:111], v99 offset:21568
	ds_read_b128 v[112:115], v99 offset:28224
	s_waitcnt lgkmcnt(2)
	v_mfma_f32_32x32x16_bf16 v[50:65], v[104:107], v[138:141], v[50:65]
	v_exp_f32_e32 v4, v4
	v_exp_f32_e32 v20, v20
	v_exp_f32_e32 v5, v5
	v_exp_f32_e32 v21, v21
	v_exp_f32_e32 v6, v6
	v_exp_f32_e32 v22, v22
	v_exp_f32_e32 v7, v7
	v_exp_f32_e32 v23, v23
	s_waitcnt lgkmcnt(1)
	v_mfma_f32_32x32x16_bf16 v[34:49], v[108:111], v[142:145], v[34:49]
	ds_read_b128 v[100:103], v99 offset:21600
	ds_read_b128 v[104:107], v99 offset:28256
	s_nop 0
	v_exp_f32_e32 v8, v8
	s_waitcnt lgkmcnt(2)
	v_mfma_f32_32x32x16_bf16 v[50:65], v[112:115], v[142:145], v[50:65]
	v_exp_f32_e32 v24, v24
	v_exp_f32_e32 v9, v9
	v_exp_f32_e32 v25, v25
	s_waitcnt lgkmcnt(1)
	v_mfma_f32_32x32x16_bf16 v[34:49], v[100:103], v[146:149], v[34:49]
	ds_read_b128 v[108:111], v99 offset:21632
	ds_read_b128 v[112:115], v99 offset:28288
	s_nop 0
	v_exp_f32_e32 v10, v10
	s_waitcnt lgkmcnt(2)
	v_mfma_f32_32x32x16_bf16 v[50:65], v[104:107], v[146:149], v[50:65]
	v_exp_f32_e32 v26, v26
	v_exp_f32_e32 v11, v11
	v_exp_f32_e32 v27, v27
	s_waitcnt lgkmcnt(1)
	v_mfma_f32_32x32x16_bf16 v[34:49], v[108:111], v[150:153], v[34:49]
	ds_read_b128 v[100:103], v99 offset:21664
	ds_read_b128 v[104:107], v99 offset:28320
	s_waitcnt lgkmcnt(2)
; #define LAS __attribute__((address_space(3)))
; __device__ __forceinline__ void att_qk_exp(const LAS char* kb, const bf16x8 (&qf)[6], float nm, fa::f32x16& n0, fa::f32x16& n1, fa::f32x16& p0, fa::f32x16& p1, float& lsum, bf16x8 (&pf)[4]) {
;     const fa::f32x16 zero = {0.f, 0.f, 0.f, 0.f, 0.f, 0.f, 0.f, 0.f, 0.f, 0.f, 0.f, 0.f, 0.f, 0.f, 0.f, 0.f};
;     bf16x8 kc0 = *(const LAS bf16x8*)kb, kc1 = *(const LAS bf16x8*)(kb + 32 * fa::KP_A);
;     float ps = 0.f, ps2 = 0.f;
; #pragma unroll
;     for (int st = 0; st < 6; ++st) {
;         bf16x8 kn0 = kc0, kn1 = kc1;
;         if (st < 5) { kn0 = *(const LAS bf16x8*)(kb + 32 * (st + 1)); kn1 = *(const LAS bf16x8*)(kb + 32 * fa::KP_A + 32 * (st + 1)); }
;         n0 = __builtin_amdgcn_mfma_f32_32x32x16_bf16(kc0, qf[st], st == 0 ? zero : n0, 0, 0, 0);
;         n1 = __builtin_amdgcn_mfma_f32_32x32x16_bf16(kc1, qf[st], st == 0 ? zero : n1, 0, 0, 0);
;         constexpr int lo[7] = {0, 2, 6, 8, 10, 14, 16};
; #pragma unroll
;         for (int r = lo[st]; r < lo[st + 1]; ++r) {
;             p0[r] = __builtin_amdgcn_exp2f(vadd1(p0[r], nm)); p1[r] = __builtin_amdgcn_exp2f(vadd1(p1[r], nm));
;             ps += p0[r]; ps += p1[r]; }
;         kc0 = kn0; kc1 = kn1;
;         __builtin_amdgcn_sched_barrier(0);
;     }
;     lsum += ps + ps2;
;     pf[0] = fa::pack_p(p0, 0); pf[1] = fa::pack_p(p0, 8); pf[2] = fa::pack_p(p1, 0); pf[3] = fa::pack_p(p1, 8);
; }
; __device__ __forceinline__ void att_exp_pack(fa::f32x16& p0, fa::f32x16& p1, float nm, float& lsum, bf16x8 (&pf)[4]) {
;     float ps = 0.f, ps2 = 0.f;
; #pragma unroll
;     for (int r = 0; r < 16; ++r) { p0[r] = __builtin_amdgcn_exp2f(vadd1(p0[r], nm)); p1[r] = __builtin_amdgcn_exp2f(vadd1(p1[r], nm)); ps += p0[r]; ps += p1[r]; }
;     lsum += ps + ps2;
;     pf[0] = fa::pack_p(p0, 0); pf[1] = fa::pack_p(p0, 8); pf[2] = fa::pack_p(p1, 0); pf[3] = fa::pack_p(p1, 8);
; }
; __device__ __forceinline__ float att_pv_max(fa::f32x16& o0, fa::f32x16& o1, const LAS char* vb, const bf16x8 (&pf)[4], const fa::f32x16& n0, const fa::f32x16& n1) {
;     using namespace fa;
;     float ta = n0[0], tb = n1[0];
;     s16x4 a0 = vtr(vb), a1 = vtr(vb + 512), b0 = vtr(vb + 4096), b1 = vtr(vb + 4096 + 512);
; #pragma unroll
;     for (int ks = 0; ks < 4; ++ks) {
;         s16x4 na0 = a0, na1 = a1, nb0 = b0, nb1 = b1;
	v_mfma_f32_32x32x16_bf16 v[50:65], v[112:115], v[150:153], v[50:65]
	v_exp_f32_e32 v12, v12
	v_exp_f32_e32 v28, v28
	v_exp_f32_e32 v13, v13
	v_exp_f32_e32 v29, v29
	v_exp_f32_e32 v14, v14
	v_exp_f32_e32 v30, v30
	v_exp_f32_e32 v15, v15
	v_exp_f32_e32 v31, v31
	v_add_f32_e32 v99, 0, v2
	v_add_f32_e32 v99, v18, v99
	v_add_f32_e32 v99, v99, v3
	v_add_f32_e32 v99, v19, v99
	v_add_f32_e32 v99, v99, v4
	v_add_f32_e32 v99, v20, v99
	v_add_f32_e32 v99, v99, v5
	v_add_f32_e32 v99, v21, v99
	v_add_f32_e32 v99, v99, v6
	v_add_f32_e32 v99, v22, v99
	v_add_f32_e32 v99, v99, v7
	v_add_f32_e32 v99, v23, v99
	v_add_f32_e32 v99, v99, v8
	v_add_f32_e32 v99, v24, v99
	v_add_f32_e32 v99, v99, v9
	v_add_f32_e32 v99, v25, v99
	v_add_f32_e32 v99, v99, v10
	v_add_f32_e32 v99, v26, v99
	v_add_f32_e32 v99, v99, v11
	v_add_f32_e32 v99, v27, v99
	v_add_f32_e32 v99, v99, v12
	v_add_f32_e32 v99, v28, v99
	v_add_f32_e32 v99, v99, v13
	v_add_f32_e32 v99, v29, v99
	v_exp_f32_e32 v16, v16
	s_waitcnt lgkmcnt(1)
	v_mfma_f32_32x32x16_bf16 v[34:49], v[100:103], v[154:157], v[34:49]
	v_add_f32_e32 v99, v99, v14
	v_exp_f32_e32 v32, v32
	v_add_f32_e32 v99, v30, v99
	v_exp_f32_e32 v17, v17
	v_add_f32_e32 v99, v99, v15
	s_waitcnt lgkmcnt(0)
	v_mfma_f32_32x32x16_bf16 v[50:65], v[104:107], v[154:157], v[50:65]
	v_exp_f32_e32 v33, v33
	v_add_f32_e32 v99, v31, v99
	v_add_f32_e32 v99, v99, v16
	v_add_f32_e32 v99, v32, v99
	v_add_f32_e32 v99, v99, v17
	v_add_f32_e32 v99, v33, v99
	v_add_u32_e32 v221, s8, v216
	v_cvt_pk_bf16_f32 v100, v2, v3
	v_cvt_pk_bf16_f32 v101, v4, v5
	v_cvt_pk_bf16_f32 v102, v6, v7
	v_cvt_pk_bf16_f32 v103, v8, v9
	v_cvt_pk_bf16_f32 v104, v10, v11
	v_cvt_pk_bf16_f32 v105, v12, v13
	v_cvt_pk_bf16_f32 v106, v14, v15
	v_cvt_pk_bf16_f32 v107, v16, v17
	v_cvt_pk_bf16_f32 v108, v18, v19
	v_cvt_pk_bf16_f32 v109, v20, v21
	v_cvt_pk_bf16_f32 v110, v22, v23
	v_cvt_pk_bf16_f32 v111, v24, v25
	v_cvt_pk_bf16_f32 v224, v26, v27
	v_cvt_pk_bf16_f32 v225, v28, v29
	v_cvt_pk_bf16_f32 v226, v30, v31
	v_cvt_pk_bf16_f32 v227, v32, v33
	ds_read_b64_tr_b16 v[112:113], v221 offset:13312
	ds_read_b64_tr_b16 v[114:115], v221 offset:13824
	ds_read_b64_tr_b16 v[116:117], v221 offset:14336
	ds_read_b64_tr_b16 v[118:119], v221 offset:14848
	s_waitcnt lgkmcnt(2)
	v_mfma_f32_32x32x16_bf16 v[82:97], v[112:115], v[100:103], v[82:97]
	ds_read_b64_tr_b16 v[112:113], v221 offset:17408
	ds_read_b64_tr_b16 v[114:115], v221 offset:17920
	ds_read_b64_tr_b16 v[120:121], v221 offset:18432
	ds_read_b64_tr_b16 v[122:123], v221 offset:18944
	v_add_f32_e32 v99, 0, v99
	v_add_f32_e32 v220, v98, v99
	s_waitcnt lgkmcnt(2)
	v_mfma_f32_32x32x16_bf16 v[66:81], v[112:115], v[100:103], v[66:81]
	s_waitcnt lgkmcnt(0)
	v_mfma_f32_32x32x16_bf16 v[66:81], v[120:123], v[104:107], v[66:81]
	ds_read_b64_tr_b16 v[98:99], v221 offset:15360
	ds_read_b64_tr_b16 v[100:101], v221 offset:15872
	ds_read_b64_tr_b16 v[112:113], v221 offset:19456
	ds_read_b64_tr_b16 v[114:115], v221 offset:19968
	v_mfma_f32_32x32x16_bf16 v[82:97], v[116:119], v[104:107], v[82:97]
	s_waitcnt lgkmcnt(0)
	v_mfma_f32_32x32x16_bf16 v[66:81], v[112:115], v[108:111], v[66:81]
	ds_read_b64_tr_b16 v[116:117], v221 offset:16384
	ds_read_b64_tr_b16 v[118:119], v221 offset:16896
	ds_read_b64_tr_b16 v[228:229], v221 offset:20480
	ds_read_b64_tr_b16 v[230:231], v221 offset:20992
	v_mfma_f32_32x32x16_bf16 v[82:97], v[98:101], v[108:111], v[82:97]
	v_max_f32_e32 v98, v51, v51
	v_max_f32_e32 v99, v50, v50
	v_max_f32_e32 v98, v99, v98
	v_max3_f32 v98, v98, v52, v53
	v_max3_f32 v98, v98, v54, v55
	v_max3_f32 v98, v98, v56, v57
	v_max3_f32 v114, v98, v58, v59
	v_max3_f32 v98, v114, v60, v61
	v_max3_f32 v99, v34, v35, v36
	s_waitcnt lgkmcnt(2)
	v_mfma_f32_32x32x16_bf16 v[82:97], v[116:119], v[224:227], v[82:97]
	v_max3_f32 v99, v99, v37, v38
	v_max3_f32 v99, v99, v39, v40
	s_waitcnt lgkmcnt(0)
	v_mfma_f32_32x32x16_bf16 v[66:81], v[228:231], v[224:227], v[66:81]
	v_max3_f32 v99, v99, v41, v42
	v_max3_f32 v99, v99, v43, v44
	v_max3_f32 v114, v99, v45, v46
	v_max3_f32 v115, v98, v62, v63
	v_max3_f32 v114, v114, v47, v48
	v_max3_f32 v115, v115, v64, v65
	v_max3_f32 v114, v114, v49, v115
	v_cmp_lt_f32_e32 vcc, 0x41000000, v114
	s_cbranch_vccz .LBB0_2993
	v_and_b32_e32 v116, 64, v1
	v_xor_b32_e32 v115, 32, v1
	v_add_u32_e32 v116, 64, v116
	v_cmp_lt_i32_e32 vcc, v115, v116
	s_nop 1
	v_cndmask_b32_e32 v115, v1, v115, vcc
	v_lshlrev_b32_e32 v115, 2, v115
	ds_bpermute_b32 v115, v115, v114
	v_max_f32_e32 v114, v114, v114
	s_waitcnt lgkmcnt(0)
; __device__ __forceinline__ bf16x8 pack_p(const f32x16& p, int base) { u32x4 w; w.x = pk2(p[base], p[base + 1]); w.y = pk2(p[base + 2], p[base + 3]); w.z = pk2(p[base + 4], p[base + 5]); w.w = pk2(p[base + 6], p[base + 7]); return __builtin_bit_cast(bf16x8, w); }
; __device__ __forceinline__ float vadd1(float a, float b) { float r; asm("v_add_f32 %0, %1, %2" : "=v"(r) : "v"(a), "v"(b)); return r; }
; __device__ __forceinline__ void att_shift(float tm, bool first, float& mrun, float& lsum, fa::f32x16& o0, fa::f32x16& o1) {
;     if (first || __any(tm > mrun + 8.f)) {
;         tm = fmaxf(tm, __shfl_xor(tm, 32));
;         const float dl = first ? 0.f : fmaxf(tm - mrun, 0.f), alpha = __builtin_amdgcn_exp2f(-dl);
;         mrun = first ? tm : mrun + dl; lsum *= alpha;
; #pragma unroll
;         for (int r = 0; r < 16; ++r) { o0[r] *= alpha; o1[r] *= alpha; }
;     }
; }
; __device__ __forceinline__ void att_exp_pack(fa::f32x16& p0, fa::f32x16& p1, float nm, float& lsum, bf16x8 (&pf)[4]) {
;     float ps = 0.f, ps2 = 0.f;
; #pragma unroll
;     for (int r = 0; r < 16; ++r) { p0[r] = __builtin_amdgcn_exp2f(vadd1(p0[r], nm)); p1[r] = __builtin_amdgcn_exp2f(vadd1(p1[r], nm)); ps += p0[r]; ps += p1[r]; }
;     lsum += ps + ps2;
;     pf[0] = fa::pack_p(p0, 0); pf[1] = fa::pack_p(p0, 8); pf[2] = fa::pack_p(p1, 0); pf[3] = fa::pack_p(p1, 8);
; }
	v_max_f32_e32 v115, v115, v115
	v_max_f32_e32 v114, v114, v115
	v_max_f32_e32 v115, 0, v114
	v_exp_f32_e64 v114, -v115
	v_add_f32_e32 v131, v131, v115
	v_mul_f32_e32 v220, v220, v114
	v_pk_mul_f32 v[96:97], v[96:97], v[114:115] op_sel_hi:[1,0]
	v_pk_mul_f32 v[94:95], v[94:95], v[114:115] op_sel_hi:[1,0]
	v_pk_mul_f32 v[92:93], v[92:93], v[114:115] op_sel_hi:[1,0]
	v_pk_mul_f32 v[90:91], v[90:91], v[114:115] op_sel_hi:[1,0]
	v_pk_mul_f32 v[88:89], v[88:89], v[114:115] op_sel_hi:[1,0]
	v_pk_mul_f32 v[86:87], v[86:87], v[114:115] op_sel_hi:[1,0]
	v_pk_mul_f32 v[84:85], v[84:85], v[114:115] op_sel_hi:[1,0]
	v_pk_mul_f32 v[82:83], v[82:83], v[114:115] op_sel_hi:[1,0]
	v_pk_mul_f32 v[80:81], v[80:81], v[114:115] op_sel_hi:[1,0]
	v_pk_mul_f32 v[78:79], v[78:79], v[114:115] op_sel_hi:[1,0]
	v_pk_mul_f32 v[76:77], v[76:77], v[114:115] op_sel_hi:[1,0]
	v_pk_mul_f32 v[74:75], v[74:75], v[114:115] op_sel_hi:[1,0]
	v_pk_mul_f32 v[72:73], v[72:73], v[114:115] op_sel_hi:[1,0]
	v_pk_mul_f32 v[70:71], v[70:71], v[114:115] op_sel_hi:[1,0]
	v_pk_mul_f32 v[68:69], v[68:69], v[114:115] op_sel_hi:[1,0]
	v_pk_mul_f32 v[66:67], v[66:67], v[114:115] op_sel_hi:[1,0]
	v_sub_f32_e32 v34, v34, v115
	v_sub_f32_e32 v35, v35, v115
	v_sub_f32_e32 v36, v36, v115
	v_sub_f32_e32 v37, v37, v115
	v_sub_f32_e32 v38, v38, v115
	v_sub_f32_e32 v39, v39, v115
	v_sub_f32_e32 v40, v40, v115
	v_sub_f32_e32 v41, v41, v115
	v_sub_f32_e32 v42, v42, v115
	v_sub_f32_e32 v43, v43, v115
	v_sub_f32_e32 v44, v44, v115
	v_sub_f32_e32 v45, v45, v115
	v_sub_f32_e32 v46, v46, v115
	v_sub_f32_e32 v47, v47, v115
	v_sub_f32_e32 v48, v48, v115
	v_sub_f32_e32 v49, v49, v115
	v_sub_f32_e32 v50, v50, v115
	v_sub_f32_e32 v51, v51, v115
	v_sub_f32_e32 v52, v52, v115
	v_sub_f32_e32 v53, v53, v115
	v_sub_f32_e32 v54, v54, v115
	v_sub_f32_e32 v55, v55, v115
	v_sub_f32_e32 v56, v56, v115
	v_sub_f32_e32 v57, v57, v115
	v_sub_f32_e32 v58, v58, v115
	v_sub_f32_e32 v59, v59, v115
	v_sub_f32_e32 v60, v60, v115
	v_sub_f32_e32 v61, v61, v115
	v_sub_f32_e32 v62, v62, v115
	v_sub_f32_e32 v63, v63, v115
	v_sub_f32_e32 v64, v64, v115
	v_sub_f32_e32 v65, v65, v115
	v_sub_f32_e32 v232, v232, v115
	v_sub_f32_e32 v233, v233, v115
	v_sub_f32_e32 v234, v234, v115
	v_sub_f32_e32 v235, v235, v115
	v_sub_f32_e32 v236, v236, v115
	v_sub_f32_e32 v237, v237, v115
	v_sub_f32_e32 v238, v238, v115
	v_sub_f32_e32 v239, v239, v115
	v_sub_f32_e32 v240, v240, v115
	v_sub_f32_e32 v241, v241, v115
	v_sub_f32_e32 v242, v242, v115
	v_sub_f32_e32 v243, v243, v115
	v_sub_f32_e32 v244, v244, v115
	v_sub_f32_e32 v245, v245, v115
	v_sub_f32_e32 v246, v246, v115
	v_sub_f32_e32 v247, v247, v115
.LBB0_2993:
	s_mov_b64 s[8:9], -1
	s_and_b64 vcc, exec, s[12:13]
	v_xor_b32_e32 v222, 0x80000000, v131
	s_barrier
	s_cbranch_vccz .LBB0_2995
	s_nop 0
	v_exp_f32_e32 v114, v34
	v_exp_f32_e32 v115, v50
	v_exp_f32_e32 v117, v35
	v_exp_f32_e32 v118, v51
	v_add_f32_e32 v116, 0, v114
	v_exp_f32_e32 v119, v36
	v_add_f32_e32 v116, v115, v116
	v_exp_f32_e32 v120, v52
	v_add_f32_e32 v116, v116, v117
	v_exp_f32_e32 v121, v37
	v_add_f32_e32 v116, v118, v116
	v_exp_f32_e32 v122, v53
	v_add_f32_e32 v116, v116, v119
	v_exp_f32_e32 v123, v38
	v_add_f32_e32 v116, v120, v116
	v_exp_f32_e32 v124, v54
	v_add_f32_e32 v116, v116, v121
	v_exp_f32_e32 v125, v39
	v_add_f32_e32 v116, v122, v116
	v_exp_f32_e32 v126, v55
	v_add_f32_e32 v116, v116, v123
	v_exp_f32_e32 v127, v40
	v_add_f32_e32 v116, v124, v116
	v_exp_f32_e32 v128, v56
	v_add_f32_e32 v116, v116, v125
	v_exp_f32_e32 v129, v41
	v_add_f32_e32 v116, v126, v116
	v_exp_f32_e32 v98, v57
	v_add_f32_e32 v116, v116, v127
	v_exp_f32_e32 v99, v42
	v_add_f32_e32 v116, v128, v116
	v_exp_f32_e32 v100, v58
	v_add_f32_e32 v116, v116, v129
	v_exp_f32_e32 v101, v43
	v_add_f32_e32 v116, v98, v116
	v_exp_f32_e32 v102, v59
	v_add_f32_e32 v116, v116, v99
	v_exp_f32_e32 v103, v44
	v_add_f32_e32 v116, v100, v116
	v_exp_f32_e32 v104, v60
	v_add_f32_e32 v116, v116, v101
	v_exp_f32_e32 v105, v45
	v_add_f32_e32 v116, v102, v116
	v_exp_f32_e32 v106, v61
	v_add_f32_e32 v116, v116, v103
	v_exp_f32_e32 v107, v46
	v_add_f32_e32 v116, v104, v116
	v_exp_f32_e32 v108, v62
	v_add_f32_e32 v116, v116, v105
	v_exp_f32_e32 v109, v47
	v_add_f32_e32 v116, v106, v116
	v_exp_f32_e32 v110, v63
	v_add_f32_e32 v116, v116, v107
	v_exp_f32_e32 v111, v48
	v_add_f32_e32 v116, v108, v116
	v_exp_f32_e32 v112, v64
	v_add_f32_e32 v116, v116, v109
	v_exp_f32_e32 v113, v49
	v_add_f32_e32 v116, v110, v116
	v_add_f32_e32 v116, v116, v111
	v_exp_f32_e32 v173, v65
	v_add_f32_e32 v116, v112, v116
	v_add_f32_e32 v116, v116, v113
	v_cvt_pk_bf16_f32 v224, v114, v117
	v_add_f32_e32 v223, v173, v116
	v_cvt_pk_bf16_f32 v225, v119, v121
	v_cvt_pk_bf16_f32 v226, v123, v125
	v_cvt_pk_bf16_f32 v227, v127, v129
	v_cvt_pk_bf16_f32 v228, v99, v101
	v_cvt_pk_bf16_f32 v229, v103, v105
	v_cvt_pk_bf16_f32 v230, v107, v109
	v_cvt_pk_bf16_f32 v231, v111, v113
	v_cvt_pk_bf16_f32 v166, v115, v118
	v_cvt_pk_bf16_f32 v167, v120, v122
	v_cvt_pk_bf16_f32 v168, v124, v126
	v_cvt_pk_bf16_f32 v169, v128, v98
	v_cvt_pk_bf16_f32 v170, v100, v102
	v_cvt_pk_bf16_f32 v171, v104, v106
	v_cvt_pk_bf16_f32 v172, v108, v110
	v_cvt_pk_bf16_f32 v173, v112, v173
	ds_read_b64_tr_b16 v[114:115], v221 offset:34816
	ds_read_b64_tr_b16 v[116:117], v221 offset:35328
	ds_read_b64_tr_b16 v[174:175], v221 offset:38912
	ds_read_b64_tr_b16 v[176:177], v221 offset:39424
	s_waitcnt lgkmcnt(2)
	v_mfma_f32_32x32x16_bf16 v[82:97], v[114:117], v[224:227], v[82:97]
	s_mov_b64 s[8:9], 0
	s_waitcnt lgkmcnt(0)
	v_mfma_f32_32x32x16_bf16 v[66:81], v[174:177], v[224:227], v[66:81]
	ds_read_b64_tr_b16 v[224:225], v221 offset:35840
	ds_read_b64_tr_b16 v[226:227], v221 offset:36352
	ds_read_b64_tr_b16 v[174:175], v221 offset:39936
	ds_read_b64_tr_b16 v[176:177], v221 offset:40448
	s_waitcnt lgkmcnt(2)
	v_mfma_f32_32x32x16_bf16 v[82:97], v[224:227], v[228:231], v[82:97]
	s_waitcnt lgkmcnt(0)
	v_mfma_f32_32x32x16_bf16 v[66:81], v[174:177], v[228:231], v[66:81]
	ds_read_b64_tr_b16 v[224:225], v221 offset:36864
	ds_read_b64_tr_b16 v[226:227], v221 offset:37376
	ds_read_b64_tr_b16 v[228:229], v221 offset:40960
	ds_read_b64_tr_b16 v[230:231], v221 offset:41472
	s_waitcnt lgkmcnt(2)
	v_mfma_f32_32x32x16_bf16 v[82:97], v[224:227], v[166:169], v[82:97]
	s_waitcnt lgkmcnt(0)
	v_mfma_f32_32x32x16_bf16 v[66:81], v[228:231], v[166:169], v[66:81]
	ds_read_b64_tr_b16 v[224:225], v221 offset:37888
	ds_read_b64_tr_b16 v[226:227], v221 offset:38400
	ds_read_b64_tr_b16 v[228:229], v221 offset:41984
	ds_read_b64_tr_b16 v[230:231], v221 offset:42496
	s_waitcnt lgkmcnt(2)
	v_mfma_f32_32x32x16_bf16 v[82:97], v[224:227], v[170:173], v[82:97]
	s_waitcnt lgkmcnt(0)
	v_mfma_f32_32x32x16_bf16 v[66:81], v[228:231], v[170:173], v[66:81]
; #define LAS __attribute__((address_space(3)))
; __device__ __forceinline__ void att_qk_exp(const LAS char* kb, const bf16x8 (&qf)[6], float nm, fa::f32x16& n0, fa::f32x16& n1, fa::f32x16& p0, fa::f32x16& p1, float& lsum, bf16x8 (&pf)[4]) {
;     const fa::f32x16 zero = {0.f, 0.f, 0.f, 0.f, 0.f, 0.f, 0.f, 0.f, 0.f, 0.f, 0.f, 0.f, 0.f, 0.f, 0.f, 0.f};
;     bf16x8 kc0 = *(const LAS bf16x8*)kb, kc1 = *(const LAS bf16x8*)(kb + 32 * fa::KP_A);
;     float ps = 0.f, ps2 = 0.f;
; #pragma unroll
;     for (int st = 0; st < 6; ++st) {
;         bf16x8 kn0 = kc0, kn1 = kc1;
;         if (st < 5) { kn0 = *(const LAS bf16x8*)(kb + 32 * (st + 1)); kn1 = *(const LAS bf16x8*)(kb + 32 * fa::KP_A + 32 * (st + 1)); }
;         n0 = __builtin_amdgcn_mfma_f32_32x32x16_bf16(kc0, qf[st], st == 0 ? zero : n0, 0, 0, 0);
;         n1 = __builtin_amdgcn_mfma_f32_32x32x16_bf16(kc1, qf[st], st == 0 ? zero : n1, 0, 0, 0);
;         constexpr int lo[7] = {0, 2, 6, 8, 10, 14, 16};
; #pragma unroll
;         for (int r = lo[st]; r < lo[st + 1]; ++r) {
;             p0[r] = __builtin_amdgcn_exp2f(vadd1(p0[r], nm)); p1[r] = __builtin_amdgcn_exp2f(vadd1(p1[r], nm));
;             ps += p0[r]; ps += p1[r]; }
;         kc0 = kn0; kc1 = kn1;
;         __builtin_amdgcn_sched_barrier(0);
;     }
;     lsum += ps + ps2;
;     pf[0] = fa::pack_p(p0, 0); pf[1] = fa::pack_p(p0, 8); pf[2] = fa::pack_p(p1, 0); pf[3] = fa::pack_p(p1, 8);
; }
; __device__ __forceinline__ void att_exp_pack(fa::f32x16& p0, fa::f32x16& p1, float nm, float& lsum, bf16x8 (&pf)[4]) {
;     float ps = 0.f, ps2 = 0.f;
; #pragma unroll
;     for (int r = 0; r < 16; ++r) { p0[r] = __builtin_amdgcn_exp2f(vadd1(p0[r], nm)); p1[r] = __builtin_amdgcn_exp2f(vadd1(p1[r], nm)); ps += p0[r]; ps += p1[r]; }
;     lsum += ps + ps2;
;     pf[0] = fa::pack_p(p0, 0); pf[1] = fa::pack_p(p0, 8); pf[2] = fa::pack_p(p1, 0); pf[3] = fa::pack_p(p1, 8);
; }
; __device__ __forceinline__ float att_pv_max(fa::f32x16& o0, fa::f32x16& o1, const LAS char* vb, const bf16x8 (&pf)[4], const fa::f32x16& n0, const fa::f32x16& n1) {
;     using namespace fa;
;     float ta = n0[0], tb = n1[0];
;     s16x4 a0 = vtr(vb), a1 = vtr(vb + 512), b0 = vtr(vb + 4096), b1 = vtr(vb + 4096 + 512);
; #pragma unroll
;     for (int ks = 0; ks < 4; ++ks) {
;         s16x4 na0 = a0, na1 = a1, nb0 = b0, nb1 = b1;
.LBB0_2995:
	s_andn2_b64 vcc, exec, s[8:9]
	s_cbranch_vccnz .LBB0_2997
	s_nop 7
	v_add_u32_e32 v98, s19, v218
	ds_read_b128 v[2:5], v98
	ds_read_b128 v[18:21], v98 offset:6656
	ds_read_b128 v[114:117], v98 offset:32
	ds_read_b128 v[118:121], v98 offset:6688
	v_exp_f32_e32 v99, v34
	v_exp_f32_e32 v100, v50
	s_waitcnt lgkmcnt(3)
	v_mfma_f32_32x32x16_bf16 v[2:17], v[2:5], v[134:137], v[232:247]
	v_exp_f32_e32 v101, v35
	v_exp_f32_e32 v102, v51
	s_waitcnt lgkmcnt(2)
	v_mfma_f32_32x32x16_bf16 v[18:33], v[18:21], v[134:137], v[232:247]
	s_waitcnt lgkmcnt(1)
	v_mfma_f32_32x32x16_bf16 v[2:17], v[114:117], v[138:141], v[2:17]
	v_exp_f32_e32 v103, v36
	ds_read_b128 v[122:125], v98 offset:64
	ds_read_b128 v[126:129], v98 offset:6720
	v_exp_f32_e32 v104, v52
	s_nop 0
	v_exp_f32_e32 v114, v37
	s_waitcnt lgkmcnt(2)
	v_mfma_f32_32x32x16_bf16 v[18:33], v[118:121], v[138:141], v[18:33]
	v_exp_f32_e32 v115, v53
	s_nop 0
	v_exp_f32_e32 v116, v38
	s_nop 0
	v_exp_f32_e32 v117, v54
	s_nop 0
	v_exp_f32_e32 v105, v39
	s_nop 0
	v_exp_f32_e32 v106, v55
	s_waitcnt lgkmcnt(1)
	v_mfma_f32_32x32x16_bf16 v[2:17], v[122:125], v[142:145], v[2:17]
	ds_read_b128 v[34:37], v98 offset:96
	ds_read_b128 v[50:53], v98 offset:6752
	v_exp_f32_e32 v118, v40
	s_nop 0
	v_exp_f32_e32 v119, v56
	s_waitcnt lgkmcnt(2)
	v_mfma_f32_32x32x16_bf16 v[18:33], v[126:129], v[142:145], v[18:33]
	v_exp_f32_e32 v120, v41
	s_nop 0
	v_exp_f32_e32 v121, v57
	s_waitcnt lgkmcnt(1)
	v_mfma_f32_32x32x16_bf16 v[2:17], v[34:37], v[146:149], v[2:17]
	ds_read_b128 v[38:41], v98 offset:128
	ds_read_b128 v[54:57], v98 offset:6784
	s_nop 0
	v_exp_f32_e32 v42, v42
	s_nop 0
	v_exp_f32_e32 v58, v58
	s_waitcnt lgkmcnt(2)
	v_mfma_f32_32x32x16_bf16 v[18:33], v[50:53], v[146:149], v[18:33]
	s_nop 0
	v_exp_f32_e32 v43, v43
	s_nop 0
	v_exp_f32_e32 v59, v59
	s_waitcnt lgkmcnt(1)
	v_mfma_f32_32x32x16_bf16 v[2:17], v[38:41], v[150:153], v[2:17]
	ds_read_b128 v[34:37], v98 offset:160
	ds_read_b128 v[50:53], v98 offset:6816
	s_nop 0
	v_exp_f32_e32 v39, v45
	s_waitcnt lgkmcnt(2)
	v_mfma_f32_32x32x16_bf16 v[18:33], v[54:57], v[150:153], v[18:33]
	v_exp_f32_e32 v61, v61
	v_exp_f32_e32 v44, v44
	v_exp_f32_e32 v40, v46
	v_exp_f32_e32 v60, v60
	v_exp_f32_e32 v62, v62
	s_nop 0
	v_exp_f32_e32 v41, v47
	s_nop 0
	v_exp_f32_e32 v63, v63
	s_waitcnt lgkmcnt(1)
	v_mfma_f32_32x32x16_bf16 v[2:17], v[34:37], v[154:157], v[2:17]
	v_exp_f32_e32 v45, v48
	s_nop 0
	v_exp_f32_e32 v54, v64
	v_mov_b32_e32 v38, v49
	v_exp_f32_e32 v49, v65
	v_add_f32_e32 v34, 0, v99
	v_add_f32_e32 v34, v100, v34
	v_add_f32_e32 v34, v34, v101
	v_add_f32_e32 v34, v102, v34
	v_add_f32_e32 v34, v34, v103
	v_add_f32_e32 v34, v104, v34
	v_add_f32_e32 v34, v34, v114
	v_add_f32_e32 v34, v115, v34
	v_add_f32_e32 v34, v34, v116
	v_add_f32_e32 v34, v117, v34
	v_add_f32_e32 v34, v34, v105
	v_add_f32_e32 v34, v106, v34
	v_add_f32_e32 v34, v34, v118
	v_add_f32_e32 v34, v119, v34
	v_add_f32_e32 v34, v34, v120
	v_add_f32_e32 v34, v121, v34
	v_add_f32_e32 v34, v34, v42
	v_add_f32_e32 v34, v58, v34
	v_add_f32_e32 v34, v34, v43
	v_add_f32_e32 v34, v59, v34
	v_add_f32_e32 v34, v34, v44
	v_add_f32_e32 v34, v60, v34
	v_add_f32_e32 v34, v34, v39
	v_add_f32_e32 v34, v61, v34
	s_waitcnt lgkmcnt(0)
	v_mfma_f32_32x32x16_bf16 v[18:33], v[50:53], v[154:157], v[18:33]
	v_add_f32_e32 v34, v34, v40
	v_add_f32_e32 v34, v62, v34
	v_exp_f32_e32 v46, v38
	v_add_f32_e32 v34, v34, v41
	v_add_f32_e32 v34, v63, v34
	v_add_f32_e32 v34, v34, v45
	v_add_f32_e32 v34, v54, v34
	v_add_f32_e32 v34, v34, v46
	v_add_f32_e32 v223, v49, v34
	v_cvt_pk_bf16_f32 v34, v99, v101
	v_cvt_pk_bf16_f32 v35, v103, v114
	v_cvt_pk_bf16_f32 v36, v116, v105
	v_cvt_pk_bf16_f32 v37, v118, v120
	v_cvt_pk_bf16_f32 v38, v42, v43
	v_cvt_pk_bf16_f32 v39, v44, v39
	v_cvt_pk_bf16_f32 v40, v40, v41
	v_cvt_pk_bf16_f32 v41, v45, v46
	v_cvt_pk_bf16_f32 v42, v100, v102
	v_cvt_pk_bf16_f32 v43, v104, v115
	v_cvt_pk_bf16_f32 v44, v117, v106
	v_cvt_pk_bf16_f32 v45, v119, v121
	v_cvt_pk_bf16_f32 v46, v58, v59
	v_cvt_pk_bf16_f32 v47, v60, v61
	v_cvt_pk_bf16_f32 v48, v62, v63
	v_cvt_pk_bf16_f32 v49, v54, v49
	ds_read_b64_tr_b16 v[50:51], v221 offset:34816
	ds_read_b64_tr_b16 v[52:53], v221 offset:35328
	ds_read_b64_tr_b16 v[54:55], v221 offset:35840
	ds_read_b64_tr_b16 v[56:57], v221 offset:36352
	s_waitcnt lgkmcnt(2)
	v_mfma_f32_32x32x16_bf16 v[82:97], v[50:53], v[34:37], v[82:97]
	ds_read_b64_tr_b16 v[50:51], v221 offset:38912
	ds_read_b64_tr_b16 v[52:53], v221 offset:39424
	ds_read_b64_tr_b16 v[58:59], v221 offset:39936
	ds_read_b64_tr_b16 v[60:61], v221 offset:40448
	s_waitcnt lgkmcnt(2)
	v_mfma_f32_32x32x16_bf16 v[66:81], v[50:53], v[34:37], v[66:81]
	ds_read_b64_tr_b16 v[34:35], v221 offset:36864
	ds_read_b64_tr_b16 v[36:37], v221 offset:37376
	ds_read_b64_tr_b16 v[50:51], v221 offset:40960
	ds_read_b64_tr_b16 v[52:53], v221 offset:41472
	v_mfma_f32_32x32x16_bf16 v[82:97], v[54:57], v[38:41], v[82:97]
	s_waitcnt lgkmcnt(4)
	v_mfma_f32_32x32x16_bf16 v[66:81], v[58:61], v[38:41], v[66:81]
	s_waitcnt lgkmcnt(2)
	v_mfma_f32_32x32x16_bf16 v[82:97], v[34:37], v[42:45], v[82:97]
	ds_read_b64_tr_b16 v[34:35], v221 offset:37888
	ds_read_b64_tr_b16 v[36:37], v221 offset:38400
	ds_read_b64_tr_b16 v[38:39], v221 offset:41984
	ds_read_b64_tr_b16 v[40:41], v221 offset:42496
	s_waitcnt lgkmcnt(4)
	v_mfma_f32_32x32x16_bf16 v[66:81], v[50:53], v[42:45], v[66:81]
	v_max_f32_e32 v42, v19, v19
	v_max_f32_e32 v43, v18, v18
	v_max_f32_e32 v42, v43, v42
	v_max3_f32 v42, v42, v20, v21
	s_waitcnt lgkmcnt(2)
	v_mfma_f32_32x32x16_bf16 v[82:97], v[34:37], v[46:49], v[82:97]
	v_max3_f32 v35, v2, v3, v4
	v_max3_f32 v42, v42, v22, v23
	v_max3_f32 v35, v35, v5, v6
	v_max3_f32 v42, v42, v24, v25
	v_max3_f32 v35, v35, v7, v8
	v_max3_f32 v34, v42, v26, v27
	v_max3_f32 v35, v35, v9, v10
	v_max3_f32 v34, v34, v28, v29
	v_max3_f32 v35, v35, v11, v12
	v_max3_f32 v35, v35, v13, v14
	v_max3_f32 v34, v34, v30, v31
	s_waitcnt lgkmcnt(0)
	v_mfma_f32_32x32x16_bf16 v[66:81], v[38:41], v[46:49], v[66:81]
	v_max3_f32 v35, v35, v15, v16
	v_max3_f32 v34, v34, v32, v33
	v_max3_f32 v201, v35, v17, v34
